# diff attention: log2e folded into the qa projection scale, running max folded into the QK MFMA C operand (no per-score fma), rescale path adjusts the -ms block
# speedup vs baseline: 1.0168x; 1.0168x over previous
; __device__ __forceinline__ void meta_proj(const Frame& F, int v) {
;     ...
;         for (int i = 0; i < 4; ++i) { const int t = 4 * (lane >> 4) + i; float val = s[i];
;             if (sec < 2) {
;                 const float o = __shfl_xor(val, 1); const int ip = (cs & 63) >> 1; const float cc = rope[(t * 32 + ip) * 2], sn = rope[(t * 32 + ip) * 2 + 1];
;                 val = (lane & 1) ? val * cc + o * sn : val * cc - o * sn;
;                 if (sec == 0) val *= 0.125f;
;             } else if (sec == 3) val *= 0.125f * LOG2E;
.LBB0_190:
	v_and_b32_e32 v0, 62, v16
	v_lshrrev_b32_e32 v8, 4, v176
	s_andn2_b64 vcc, exec, s[8:9]
	v_lshlrev_b32_e32 v0, 2, v0
	s_cbranch_vccnz .LBB0_192
	v_lshl_or_b32 v12, v8, 10, v0
	global_load_dwordx2 v[18:19], v12, s[0:1]
	v_mbcnt_lo_u32_b32 v12, -1, 0
	v_mbcnt_hi_u32_b32 v12, -1, v12
	v_and_b32_e32 v20, 64, v12
	v_xor_b32_e32 v17, 1, v12
	v_add_u32_e32 v20, 64, v20
	v_cmp_lt_i32_e32 vcc, v17, v20
	s_nop 1
	v_cndmask_b32_e32 v12, v12, v17, vcc
	v_lshlrev_b32_e32 v12, 2, v12
	ds_bpermute_b32 v12, v12, v4
	s_waitcnt vmcnt(0) lgkmcnt(0)
	v_mul_f32_e32 v12, v19, v12
	v_cndmask_b32_e64 v12, v12, -v12, s[4:5]
	v_fmac_f32_e32 v12, v4, v18
	v_mul_f32_e32 v4, 0x3e38aa3b, v12
	v_cndmask_b32_e64 v12, v12, v4, s[2:3]

; __device__ __forceinline__ void meta_proj(const Frame& F, int v) {
;     ...
;         for (int i = 0; i < 4; ++i) { const int t = 4 * (lane >> 4) + i; float val = s[i];
;             if (sec < 2) {
;                 const float o = __shfl_xor(val, 1); const int ip = (cs & 63) >> 1; const float cc = rope[(t * 32 + ip) * 2], sn = rope[(t * 32 + ip) * 2 + 1];
;                 val = (lane & 1) ? val * cc + o * sn : val * cc - o * sn;
;                 if (sec == 0) val *= 0.125f;
;             } else if (sec == 3) val *= 0.125f * LOG2E;
.LBB0_195:
	v_lshl_or_b32 v8, v5, 8, v0
	global_load_dwordx2 v[8:9], v8, s[0:1]
	v_mbcnt_lo_u32_b32 v12, -1, 0
	v_mbcnt_hi_u32_b32 v12, -1, v12
	v_and_b32_e32 v18, 64, v12
	v_xor_b32_e32 v13, 1, v12
	v_add_u32_e32 v18, 64, v18
	v_cmp_lt_i32_e32 vcc, v13, v18
	s_nop 1
	v_cndmask_b32_e32 v12, v12, v13, vcc
	v_lshlrev_b32_e32 v12, 2, v12
	ds_bpermute_b32 v12, v12, v1
	s_waitcnt vmcnt(0) lgkmcnt(0)
	v_mul_f32_e32 v9, v9, v12
	v_cndmask_b32_e64 v9, v9, -v9, s[4:5]
	v_fmac_f32_e32 v9, v1, v8
	v_mul_f32_e32 v1, 0x3e38aa3b, v9
	v_cndmask_b32_e64 v8, v9, v1, s[2:3]

; __device__ __forceinline__ void meta_proj(const Frame& F, int v) {
;     ...
;         for (int i = 0; i < 4; ++i) { const int t = 4 * (lane >> 4) + i; float val = s[i];
;             if (sec < 2) {
;                 const float o = __shfl_xor(val, 1); const int ip = (cs & 63) >> 1; const float cc = rope[(t * 32 + ip) * 2], sn = rope[(t * 32 + ip) * 2 + 1];
;                 val = (lane & 1) ? val * cc + o * sn : val * cc - o * sn;
;                 if (sec == 0) val *= 0.125f;
;             } else if (sec == 3) val *= 0.125f * LOG2E;
.LBB0_199:
	v_lshl_or_b32 v5, v2, 8, v0
	global_load_dwordx2 v[8:9], v5, s[0:1]
	v_mbcnt_lo_u32_b32 v5, -1, 0
	v_mbcnt_hi_u32_b32 v5, -1, v5
	v_and_b32_e32 v10, 64, v5
	v_xor_b32_e32 v6, 1, v5
	v_add_u32_e32 v10, 64, v10
	v_cmp_lt_i32_e32 vcc, v6, v10
	s_nop 1
	v_cndmask_b32_e32 v5, v5, v6, vcc
	v_lshlrev_b32_e32 v5, 2, v5
	ds_bpermute_b32 v5, v5, v1
	s_waitcnt vmcnt(0) lgkmcnt(0)
	v_mul_f32_e32 v5, v9, v5
	v_cndmask_b32_e64 v5, v5, -v5, s[4:5]
	v_fmac_f32_e32 v5, v1, v8
	v_mul_f32_e32 v1, 0x3e38aa3b, v5
	v_cndmask_b32_e64 v5, v5, v1, s[2:3]

; __device__ __forceinline__ void meta_proj(const Frame& F, int v) {
;     ...
;         for (int i = 0; i < 4; ++i) { const int t = 4 * (lane >> 4) + i; float val = s[i];
;             if (sec < 2) {
;                 const float o = __shfl_xor(val, 1); const int ip = (cs & 63) >> 1; const float cc = rope[(t * 32 + ip) * 2], sn = rope[(t * 32 + ip) * 2 + 1];
;                 val = (lane & 1) ? val * cc + o * sn : val * cc - o * sn;
;                 if (sec == 0) val *= 0.125f;
;             } else if (sec == 3) val *= 0.125f * LOG2E;
.LBB0_203:
	v_lshl_or_b32 v0, v2, 8, v0
	global_load_dwordx2 v[4:5], v0, s[0:1]
	v_mbcnt_lo_u32_b32 v0, -1, 0
	v_mbcnt_hi_u32_b32 v0, -1, v0
	v_and_b32_e32 v6, 64, v0
	v_xor_b32_e32 v3, 1, v0
	v_add_u32_e32 v6, 64, v6
	v_cmp_lt_i32_e32 vcc, v3, v6
	s_nop 1
	v_cndmask_b32_e32 v0, v0, v3, vcc
	v_lshlrev_b32_e32 v0, 2, v0
	ds_bpermute_b32 v0, v0, v1
	s_waitcnt vmcnt(0) lgkmcnt(0)
	v_mul_f32_e32 v0, v5, v0
	v_cndmask_b32_e64 v0, v0, -v0, s[4:5]
	v_fmac_f32_e32 v0, v1, v4
	v_mul_f32_e32 v1, 0x3e38aa3b, v0
	v_cndmask_b32_e64 v3, v0, v1, s[2:3]

; #define PG8_WAIT_V(n) asm volatile("s_waitcnt vmcnt(" #n ")" ::: "memory")
; #define PG8_BAR __builtin_amdgcn_s_barrier()
; template <class Epi, class Sched, bool ALIGN_EPI = false, bool SP2 = false>
; __device__ __forceinline__ void gemm_phase(PG8_LAS unsigned char* lds, const Gemm g, const Sched& S, const Epi& E) {
;     const int tid = threadIdx.x, wid = __builtin_amdgcn_readfirstlane(tid >> 6), lane = tid & 63, wr = wid >> 2, wc = wid & 3, fr = lane & 15, fq = lane >> 4;
;     const int K = g.K, nt = K / BK;
;     unsigned voffA[2], voffB[2];
; #pragma unroll
;     for (int i = 0; i < 2; ++i) { int R, C; stage_rc(tid * 16 + i * 8192, R, C); const int Rb = Epi::PERM ? (64 * (R >> 5) + perm32(R & 31)) : R;
;         voffA[i] = (unsigned)(R * K + C) * 2u; voffB[i] = (unsigned)(Rb * K + C) * 2u; }
;     const size_t kstep = (size_t)(BK * 2);
;     const size_t hstep = (size_t)HALF * K * 2;
;     const size_t tstep = 2 * hstep;
;     const size_t hstepB = Epi::PERM ? (size_t)32 * K * 2 : hstep;
;     const unsigned ldsw = (unsigned)wid * 1024u;
;     const int aoff = lds_byte(wr * 64 + fr, fq * 8), boff = lds_byte(wc * 32 + fr, fq * 8);
;     ...
;     Unit cur, nxt; int ui = 0;
;     if (!S.next(0, cur)) return;
;     f32x4 acc[2][2][4][2];
; #pragma unroll
;     for (int a = 0; a < 2; ++a)
; #pragma unroll
;         for (int b = 0; b < 2; ++b)
; #pragma unroll
;             for (int m = 0; m < 4; ++m)
; #pragma unroll
;                 for (int n = 0; n < 2; ++n) acc[a][b][m][n] = (f32x4){0.f, 0.f, 0.f, 0.f};
;     bf16x8 At[4][2], B0[2][2], B1[2][2];
;     const char* cA = g.a_ptr(cur.pm); const char* cB = (const char*)g.Bt + (size_t)cur.pn * tstep;
;     S.a_ready(cur);
;     if constexpr (SP2) {
;         PG8_STAGE(PG8_SB(0, 0), cB, voffB); PG8_STAGE(PG8_SB(0, 1), cB + hstepB, voffB); PG8_STAGE(PG8_SA(0, 0), cA, voffA); PG8_STAGE(PG8_SA(0, 1), cA + hstep, voffA);
;         if (wr == 1) PG8_BAR;
;         PG8_WAIT_V(2); PG8_BAR;
;         PG8_STAGE(PG8_SB(1, 0), cB + kstep, voffB); PG8_STAGE(PG8_SA(1, 0), cA + kstep, voffA); PG8_STAGE(PG8_SB(1, 1), cB + hstepB + kstep, voffB);
;         PG8_WAIT_V(6); PG8_BAR;
;     } else {
;         PG8_STAGE(PG8_SB(0, 0), cB, voffB); PG8_STAGE(PG8_SA(0, 0), cA, voffA); PG8_STAGE(PG8_SB(0, 1), cB + hstepB, voffB); PG8_STAGE(PG8_SA(0, 1), cA + hstep, voffA);
;         if (wr == 1) PG8_BAR;
;         PG8_WAIT_V(4); PG8_BAR;
.LBB0_209:
	s_add_u32 s8, s82, 0x400000
	s_addc_u32 s9, s83, 0
	s_and_b32 s1, s14, 3
	s_mov_b64 s[14:15], 0x80
	s_add_i32 m0, s55, 0x18000
	v_lshl_add_u64 v[6:7], v[6:7], 0, s[14:15]
	s_ashr_i32 s61, s70, 31
	s_lshl_b32 s62, s4, 6
	s_lshl_b32 s18, s4, 13
	s_lshl_b32 s19, s1, 12
	s_waitcnt vmcnt(2)
	s_barrier
	global_load_lds_dwordx4 v[6:7], off
	v_lshl_add_u64 v[4:5], v[4:5], 0, s[14:15]
	s_add_i32 m0, s55, 0x1a000
	s_add_i32 s63, s55, 0x8000
	s_add_i32 s64, s55, 0xa000
	global_load_lds_dwordx4 v[4:5], off
	v_lshl_add_u64 v[2:3], v[2:3], 0, s[14:15]
	s_mov_b32 m0, s63
	s_add_u32 s16, s44, 0x10080
	global_load_lds_dwordx4 v[2:3], off
	v_lshl_add_u64 v[0:1], v[0:1], 0, s[14:15]
	s_mov_b32 m0, s64
	s_addc_u32 s17, s45, 0
	global_load_lds_dwordx4 v[0:1], off
	s_add_i32 m0, s55, 0x1c000
	v_lshl_add_u64 v[0:1], s[16:17], 0, v[166:167]
	global_load_lds_dwordx4 v[0:1], off
	v_lshl_add_u64 v[0:1], s[16:17], 0, v[170:171]
	s_add_i32 m0, s55, 0x1e000
	s_sext_i32_i16 s90, s2
	global_load_lds_dwordx4 v[0:1], off
	v_bfe_u32 v0, v177, 4, 2
	v_lshlrev_b32_e32 v190, 3, v0
	v_lshlrev_b32_e32 v191, 4, v0
	v_lshlrev_b32_e32 v0, 6, v177
	s_movk_i32 s2, 0x3c0
	v_lshlrev_b32_e32 v6, 6, v189
	s_cmpk_lt_u32 s3, 0x100
	v_and_or_b32 v1, v0, s2, v191
	v_and_or_b32 v6, v6, s2, v191
	s_cselect_b64 s[16:17], -1, 0
	s_lshl_b32 s2, s4, 2
	s_lshl_b32 s66, s1, 6
	s_or_b32 s1, s2, s1
	s_mulk_i32 s1, 0x900
	v_lshlrev_b32_e32 v0, 2, v177
	s_add_i32 s1, s1, 0
	v_and_b32_e32 v3, 32, v0
	s_add_i32 s1, s1, 0x20400
	s_movk_i32 s20, 0x90
	v_bitop3_b32 v193, s19, v1, v3 bitop3:0xf6
	v_mov_b32_e32 v1, s1
	v_mad_u32_u24 v194, v189, s20, v1
	v_lshlrev_b32_e32 v1, 8, v177
	v_and_b32_e32 v1, 0x38000, v1
	v_lshlrev_b32_e32 v3, 11, v10
	v_or3_b32 v1, v8, v1, v3
	v_and_b32_e32 v2, 7, v12
	v_lshlrev_b32_e32 v7, 2, v189
	v_add_u32_e32 v174, v1, v9
	v_lshlrev_b32_e32 v1, 4, v11
	v_and_b32_e32 v5, 7, v177
	v_mul_u32_u24_e32 v192, 0x90, v2
	v_lshlrev_b32_e32 v2, 10, v2
	v_and_b32_e32 v7, 32, v7
	s_waitcnt vmcnt(6)
	v_and_b32_e32 v1, 0x78000, v1
	v_lshlrev_b32_e32 v0, 3, v5
	v_or_b32_e32 v4, 0x2000, v2
	v_bitop3_b32 v6, v6, s18, v7 bitop3:0xde
	v_or3_b32 v1, v8, v1, v3
	s_add_i32 s67, 0, 0x10000
	s_add_i32 s72, 0, 0x14000
	s_mov_b32 s65, s70
	v_lshl_add_u32 v195, v5, 4, s1
	v_mov_b32_e32 v175, v173
	v_add_u32_e32 v178, v1, v9
	v_mov_b32_e32 v179, v173
	s_mov_b64 s[18:19], 0x1000
	v_mov_b64_e32 v[180:181], 0x1000
	v_mov_b64_e32 v[182:183], 0xfff
	v_add_u32_e32 v196, s67, v193
	v_add_u32_e32 v197, s72, v193
	v_add_u32_e32 v198, 0, v6
	s_mov_b32 s73, 0x3f3c0
	s_mov_b64 s[20:21], 0x1080
	s_mov_b64 s[22:23], 0x2000
	s_mov_b64 s[24:25], 0x2080
	s_mov_b64 s[26:27], 0x3000
	s_movk_i32 s74, 0x3000
	s_mov_b64 s[28:29], 0x3080
	s_mov_b64 s[30:31], 0x4000
	s_mov_b64 s[34:35], 0x4080
	v_lshlrev_b32_e32 v172, 1, v0
	v_lshlrev_b32_e32 v184, 1, v2
	v_lshlrev_b32_e32 v186, 1, v4
	v_mov_b32_e32 v199, 0x3e38aa3b
	v_mov_b32_e32 v200, 0x3e38aa3b
	s_mov_b32 s75, 0
	s_barrier
	s_branch .LBB0_212

; __device__ __forceinline__ void diff_unit(const Frame& F, int b, int h, int qi, float lam, int dry) {
;     ...
;     bf16* QA = (bf16*)(F.ws + WS_SEC); const bf16* KA = QA + SEC_ELEMS; const bf16* VA = QA + 2 * SEC_ELEMS;
;     bf16x8 qf[4];
;     { const bf16* qp = QA + (rowbase + tq) * 1024 + 128 * h + 64 * map + 8 * hi;
; #pragma unroll
;       for (int ks = 0; ks < 4; ++ks) qf[ks] = *(const bf16x8*)(qp + 16 * ks); }
;     const int srow = tid >> 4, sc16 = tid & 15;
;     const bf16* kg = KA + (rowbase + srow) * 1024 + 128 * h + sc16 * 8;
;     const bf16* vg = VA + (rowbase + srow) * 1024 + 128 * h + sc16 * 8;
;     const int klds = D_KOFF + srow * DK_STR + sc16 * 16, vlds = D_VOFF + srow * DV_STR + sc16 * 16;
;     u32x4 st0, st1, st2, st3;
;     ...
;     const int nt = 2 * qi + 3;
;     __syncthreads();
;     D_LOAD(0); D_STORE(0);
;     __syncthreads();
;     f32x16 O[4];
; #pragma unroll
;     for (int dt = 0; dt < 4; ++dt)
; #pragma unroll
;         for (int r = 0; r < 16; ++r) O[dt][r] = 0.f;
;     float ms = -INFINITY, lsum = 0.f;
;     const int kra = D_KOFF + r32 * DK_STR + map * 128 + hi * 16;
;     const int vra = D_VOFF + (4 * hi + ((lane & 15) >> 2)) * DV_STR + (16 * ((lane >> 4) & 1) + 4 * (lane & 3)) * 2;
;     for (int it = 0; it < nt; ++it) {
;         const int key0 = it == 0 ? 0 : NMETA + 64 * (it - 1);
;         if (it + 1 < nt) D_LOAD(NMETA + 64 * it);
;         const bool meta = (it == 0);
;         if (meta || key0 <= tqw + 31) {
;             const LAS unsigned char* kb = lds + kra + (it & 1) * DK_BUF;
;             const LAS unsigned char* vb = lds + vra + (it & 1) * DV_BUF;
;             f32x16 s0, s1;
; #pragma unroll
;             for (int r = 0; r < 16; ++r) { s0[r] = 0.f; s1[r] = 0.f; }
;             bf16x8 vpre0 = VFRAG(vb, 0, DV_STR), vpre1 = VFRAG(vb, 64, DV_STR), vpre2 = VFRAG(vb, 128, DV_STR), vpre3 = VFRAG(vb, 192, DV_STR);
;             bf16x8 vprf0 = VFRAG(vb, 16 * DV_STR, DV_STR), vprf1 = VFRAG(vb, 16 * DV_STR + 64, DV_STR);
;             __builtin_amdgcn_s_setprio(1);
; #pragma unroll
;             for (int ks = 0; ks < 4; ++ks) { const bf16x8 k0 = *(const LAS bf16x8*)(kb + ks * 32); s0 = MFMA32(k0, qf[ks], s0); }
;             if (!meta) {
; #pragma unroll
;                 for (int ks = 0; ks < 4; ++ks) { const bf16x8 k1 = *(const LAS bf16x8*)(kb + 32 * DK_STR + ks * 32); s1 = MFMA32(k1, qf[ks], s1); }
;             }
.LBB0_292:
	s_and_b32 s90, s83, 15
	s_lshl_b32 s1, s90, 7
	v_readlane_b32 s2, v254, 56
	s_or_b32 s70, s2, s1
	s_or_b32 s1, s70, 16
	s_ashr_i32 s0, s83, 7
	v_add_u32_e32 v158, s1, v204
	v_writelane_b32 v254, s1, 63
	v_mad_i64_i32 v[0:1], s[2:3], s0, v220, v[158:159]
	v_readlane_b32 s2, v254, 32
	s_lshl_b32 s1, s83, 3
	v_lshlrev_b64 v[0:1], 11, v[0:1]
	v_readlane_b32 s3, v254, 33
	s_and_b32 s1, s1, 0x380
	s_lshl_b32 s74, s1, 1
	v_lshl_add_u64 v[0:1], s[2:3], 0, v[0:1]
	v_lshl_add_u64 v[0:1], v[0:1], 0, s[74:75]
	s_mov_b32 s95, s75
	v_lshl_add_u64 v[0:1], v[0:1], 0, s[94:95]
	v_mov_b32_e32 v153, v159
	v_lshl_add_u64 v[0:1], v[0:1], 0, v[152:153]
	global_load_dwordx4 v[96:99], v[0:1], off
	global_load_dwordx4 v[100:103], v[0:1], off offset:32
	global_load_dwordx4 v[104:107], v[0:1], off offset:64
	global_load_dwordx4 v[108:111], v[0:1], off offset:96
	v_mad_i64_i32 v[0:1], s[2:3], s0, v220, v[160:161]
	v_readlane_b32 s2, v254, 47
	v_lshlrev_b64 v[0:1], 11, v[0:1]
	v_readlane_b32 s3, v254, 48
	v_mov_b32_e32 v185, v159
	s_mov_b32 s1, 0x10000
	v_lshl_add_u64 v[2:3], s[2:3], 0, v[0:1]
	v_readlane_b32 s2, v254, 49
	v_readlane_b32 s3, v254, 50
	v_lshl_add_u64 v[2:3], v[2:3], 0, s[74:75]
	v_lshl_add_u64 v[188:189], v[2:3], 0, v[184:185]
	v_lshl_add_u64 v[0:1], s[2:3], 0, v[0:1]
	v_lshl_add_u64 v[0:1], v[0:1], 0, s[74:75]
	v_lshl_add_u64 v[190:191], v[0:1], 0, v[184:185]
	v_add_co_u32_e32 v0, vcc, s1, v188
	s_nop 1
	v_addc_co_u32_e32 v1, vcc, 0, v189, vcc
	global_load_dwordx4 v[0:3], v[0:1], off
	s_nop 0
	global_load_dwordx4 v[4:7], v[188:189], off
	global_load_dwordx4 v[8:11], v[190:191], off
	v_add_co_u32_e32 v12, vcc, s1, v190
	s_mov_b32 s1, 0x8000
	s_nop 0
	v_addc_co_u32_e32 v13, vcc, 0, v191, vcc
	global_load_dwordx4 v[12:15], v[12:13], off
	v_add_co_u32_e32 v16, vcc, s1, v188
	s_mov_b32 s2, 0x18000
	s_nop 0
	v_addc_co_u32_e32 v17, vcc, 0, v189, vcc
	v_add_co_u32_e32 v18, vcc, s2, v188
	s_nop 1
	v_addc_co_u32_e32 v19, vcc, 0, v189, vcc
	v_add_co_u32_e32 v20, vcc, s1, v190
	s_nop 1
	v_addc_co_u32_e32 v21, vcc, 0, v191, vcc
	v_add_co_u32_e32 v22, vcc, s2, v190
	s_nop 1
	v_addc_co_u32_e32 v23, vcc, 0, v191, vcc
	global_load_dwordx4 v[112:115], v[16:17], off
	global_load_dwordx4 v[116:119], v[18:19], off
	global_load_dwordx4 v[120:123], v[20:21], off
	global_load_dwordx4 v[124:127], v[22:23], off
	s_barrier
	s_waitcnt vmcnt(6)
	ds_write_b128 v209, v[4:7]
	ds_write_b128 v209, v[0:3] offset:8704
	s_waitcnt vmcnt(5)
	ds_write_b128 v210, v[8:11] offset:34816
	s_waitcnt vmcnt(4)
	ds_write_b128 v210, v[12:15] offset:45056
	s_waitcnt lgkmcnt(0)
	s_barrier
	ds_read_b64_tr_b16 v[32:33], v213 offset:34816
	ds_read_b64_tr_b16 v[64:65], v213 offset:34880
	ds_read_b64_tr_b16 v[72:73], v213 offset:34944
	ds_read_b64_tr_b16 v[68:69], v213 offset:35008
	ds_read_b64_tr_b16 v[34:35], v213 offset:37376
	ds_read_b64_tr_b16 v[66:67], v213 offset:37440
	ds_read_b64_tr_b16 v[74:75], v213 offset:37504
	ds_read_b64_tr_b16 v[70:71], v213 offset:37568
	s_setprio 1
	ds_read_b128 v[0:3], v212
	ds_read_b128 v[4:7], v212 offset:32
	s_waitcnt lgkmcnt(1)
	v_mfma_f32_32x32x16_bf16 v[16:31], v[0:3], v[96:99], 0
	s_waitcnt lgkmcnt(0)
	v_mfma_f32_32x32x16_bf16 v[16:31], v[4:7], v[100:103], v[16:31]
	ds_read_b128 v[0:3], v212 offset:64
	ds_read_b128 v[4:7], v212 offset:96
	s_waitcnt lgkmcnt(1)
	v_mfma_f32_32x32x16_bf16 v[16:31], v[0:3], v[104:107], v[16:31]
	s_waitcnt lgkmcnt(0)
	v_mfma_f32_32x32x16_bf16 v[16:31], v[4:7], v[108:111], v[16:31]
	s_setprio 0
	s_nop 10
	v_max_f32_e32 v0, v16, v16
	v_max_f32_e32 v1, v17, v17
	v_max_f32_e32 v2, v18, v18
	v_max_f32_e32 v0, 0xff800000, v0
	v_max_f32_e32 v1, 0xff800000, v1
	v_max_f32_e32 v2, 0xff800000, v2
	v_max3_f32 v0, v0, v1, v2
	v_max_f32_e32 v1, v19, v19
	v_max_f32_e32 v2, v20, v20
	v_max_f32_e32 v1, 0xff800000, v1
	v_max_f32_e32 v2, 0xff800000, v2
	v_max3_f32 v0, v0, v1, v2
	v_max_f32_e32 v1, v21, v21
	v_max_f32_e32 v2, v22, v22
	v_max_f32_e32 v1, 0xff800000, v1
	v_max_f32_e32 v2, 0xff800000, v2
	v_max3_f32 v0, v0, v1, v2
	v_max_f32_e32 v1, v23, v23
	v_max_f32_e32 v1, 0xff800000, v1
	s_mov_b32 s1, 0xff800000
	v_max3_f32 v0, v0, v1, s1
	ds_bpermute_b32 v1, v155, v0
	s_waitcnt lgkmcnt(0)
	v_max_f32_e32 v1, v1, v1
	v_max_f32_e32 v0, v0, v1
	v_cmp_neq_f32_e32 vcc, s1, v0
	s_cbranch_vccz .LBB0_294
	v_max_f32_e32 v0, v0, v0
	v_max_f32_e32 v185, 0xff800000, v0
	v_sub_f32_e32 v0, 0xff800000, v185
	v_exp_f32_e32 v0, v0
	s_nop 0
	v_mul_f32_e32 v1, 0, v0
	v_mov_b32_e32 v0, v1
	s_branch .LBB0_295

; #define MFMA32(a, b, c) __builtin_amdgcn_mfma_f32_32x32x16_bf16((a), (b), (c), 0, 0, 0)
; #define VFRAG(ptr, off0, STR) ({ const s16x4 lo_ = vtr((ptr) + (off0)); const s16x4 hi_ = vtr((ptr) + (off0) + 8 * (STR)); (bf16x8){lo_[0], lo_[1], lo_[2], lo_[3], hi_[0], hi_[1], hi_[2], hi_[3]}; })
; #define D_STORE(buf) do { *(LAS u32x4*)(lds + klds + (buf) * DK_BUF) = st0; *(LAS u32x4*)(lds + klds + (buf) * DK_BUF + 32 * DK_STR) = st1; *(LAS u32x4*)(lds + vlds + (buf) * DV_BUF) = st2; *(LAS u32x4*)(lds + vlds + (buf) * DV_BUF + 32 * DV_STR) = st3; } while (0)
; __device__ __forceinline__ void diff_unit(const Frame& F, int b, int h, int qi, float lam, int dry) {
;     ...
;                 const float msn = fmaxf(ms, mxs); const float f = __builtin_amdgcn_exp2f(ms - msn); lsum *= f; ms = msn;
; #pragma unroll
;                 for (int dt = 0; dt < 4; ++dt)
; #pragma unroll
;                     for (int r = 0; r < 16; ++r) O[dt][r] *= f;
;             }
;             float ps = 0.f;
; #pragma unroll
;             for (int r = 0; r < 16; ++r) { s0[r] = __builtin_amdgcn_exp2f(s0[r] * LOG2E - ms); ps += s0[r]; }
;             if (!meta) {
; #pragma unroll
;                 for (int r = 0; r < 16; ++r) { s1[r] = __builtin_amdgcn_exp2f(s1[r] * LOG2E - ms); ps += s1[r]; }
;             }
;             lsum += ps;
;             __builtin_amdgcn_s_setprio(1);
;             { const bf16x8 pf = pack_step(s0, 0);
;               O[0] = MFMA32(vpre0, pf, O[0]); O[1] = MFMA32(vpre1, pf, O[1]); O[2] = MFMA32(vpre2, pf, O[2]); O[3] = MFMA32(vpre3, pf, O[3]); }
;             if (!meta) {
;                 { const bf16x8 pf = pack_step(s0, 1);
;                   O[0] = MFMA32(vprf0, pf, O[0]); O[1] = MFMA32(vprf1, pf, O[1]);
; #pragma unroll
;                   for (int dt = 2; dt < 4; ++dt) { const bf16x8 vf = VFRAG(vb, 16 * DV_STR + 64 * dt, DV_STR); O[dt] = MFMA32(vf, pf, O[dt]); } }
; #pragma unroll
;                 for (int s2 = 0; s2 < 2; ++s2) { const bf16x8 pf = pack_step(s1, s2);
; #pragma unroll
;                     for (int dt = 0; dt < 4; ++dt) { const bf16x8 vf = VFRAG(vb, (32 + 16 * s2) * DV_STR + 64 * dt, DV_STR); O[dt] = MFMA32(vf, pf, O[dt]); } }
;             }
;             __builtin_amdgcn_s_setprio(0);
;         }
;         if (it + 1 < nt) D_STORE((it + 1) & 1);
.LBB0_295:
	v_sub_f32_e32 v238, 0, v185
	v_sub_f32_e32 v239, 0, v185
	v_sub_f32_e32 v240, 0, v185
	v_sub_f32_e32 v241, 0, v185
	v_sub_f32_e32 v242, 0, v185
	v_sub_f32_e32 v243, 0, v185
	v_sub_f32_e32 v244, 0, v185
	v_sub_f32_e32 v245, 0, v185
	v_sub_f32_e32 v246, 0, v185
	v_sub_f32_e32 v247, 0, v185
	v_sub_f32_e32 v248, 0, v185
	v_sub_f32_e32 v249, 0, v185
	v_sub_f32_e32 v250, 0, v185
	v_sub_f32_e32 v251, 0, v185
	v_sub_f32_e32 v252, 0, v185
	v_sub_f32_e32 v253, 0, v185
	v_sub_f32_e32 v16, v16, v185
	v_exp_f32_e32 v16, v16
	v_sub_f32_e32 v17, v17, v185
	v_exp_f32_e32 v17, v17
	v_sub_f32_e32 v18, v18, v185
	v_exp_f32_e32 v18, v18
	v_sub_f32_e32 v19, v19, v185
	v_exp_f32_e32 v19, v19
	v_sub_f32_e32 v20, v20, v185
	v_add_f32_e32 v24, 0, v16
	v_exp_f32_e32 v20, v20
	v_sub_f32_e32 v21, v21, v185
	v_add_f32_e32 v24, v17, v24
	v_exp_f32_e32 v21, v21
	v_sub_f32_e32 v22, v22, v185
	v_add_f32_e32 v24, v18, v24
	v_exp_f32_e32 v22, v22
	v_sub_f32_e32 v23, v23, v185
	v_add_f32_e32 v24, v19, v24
	v_exp_f32_e32 v23, v23
	v_sub_f32_e32 v25, 0xff800000, v185
	v_add_f32_e32 v24, v20, v24
	v_exp_f32_e32 v25, v25
	v_add_f32_e32 v24, v21, v24
	v_add_f32_e32 v24, v22, v24
	v_add_f32_e32 v24, v23, v24
	v_add_f32_e32 v24, v25, v24
	v_add_f32_e32 v24, v25, v24
	v_add_f32_e32 v24, v25, v24
	v_add_f32_e32 v24, v25, v24
	s_mov_b64 s[2:3], 0x10000
	v_add_f32_e32 v24, v25, v24
	v_lshl_add_u64 v[200:201], v[188:189], 0, s[2:3]
	v_lshl_add_u64 v[202:203], v[190:191], 0, s[2:3]
	s_mov_b64 s[2:3], 0x8000
	s_lshl_b32 s1, s33, 1
	v_add_f32_e32 v24, v25, v24
	v_lshl_add_u64 v[192:193], v[188:189], 0, s[2:3]
	v_lshl_add_u64 v[196:197], v[190:191], 0, s[2:3]
	s_and_b32 s2, s1, 0x700
	s_and_b32 s1, s82, 15
	v_add_f32_e32 v24, v25, v24
	s_mov_b64 s[4:5], 0x18000
	v_lshl_add_u32 v153, s1, 7, v217
	s_lshl_b32 s1, s1, 18
	s_lshl_b32 s95, s90, 1
	v_add_f32_e32 v24, v25, v24
	v_mov_b32_e32 v2, v1
	v_mov_b32_e32 v3, v1
	v_mov_b32_e32 v4, v1
	v_mov_b32_e32 v5, v1
	v_mov_b32_e32 v6, v1
	v_mov_b32_e32 v7, v1
	v_mov_b32_e32 v8, v1
	v_mov_b32_e32 v9, v1
	v_mov_b32_e32 v10, v1
	v_mov_b32_e32 v11, v1
	v_mov_b32_e32 v12, v1
	v_mov_b32_e32 v13, v1
	v_mov_b32_e32 v14, v1
	v_mov_b32_e32 v15, v1
	s_mul_hi_i32 s73, s0, 0x1010
	s_mul_i32 s72, s0, 0x1010
	v_lshl_add_u64 v[194:195], v[188:189], 0, s[4:5]
	v_lshl_add_u64 v[198:199], v[190:191], 0, s[4:5]
	s_add_u32 s89, s1, 0x40000
	s_add_i32 s95, s95, 3
	s_or_b32 s10, s70, 1
	s_addk_i32 s70, 0x5f
	v_add_f32_e32 v158, v1, v24
	s_setprio 1
	v_cvt_pk_bf16_f32 v76, v16, v17
	v_cvt_pk_bf16_f32 v77, v18, v19
	v_cvt_pk_bf16_f32 v78, v20, v21
	v_cvt_pk_bf16_f32 v79, v22, v23
	s_nop 1
	v_mfma_f32_32x32x16_bf16 v[48:63], v[32:35], v[76:79], v[0:15]
	v_mfma_f32_32x32x16_bf16 v[32:47], v[64:67], v[76:79], v[0:15]
	v_mfma_f32_32x32x16_bf16 v[16:31], v[72:75], v[76:79], v[0:15]
	v_mfma_f32_32x32x16_bf16 v[0:15], v[68:71], v[76:79], v[0:15]
	s_setprio 0
	s_mul_hi_i32 s1, s0, 0x808000
	s_mul_i32 s0, s0, 0x808000
	s_or_b32 s0, s0, s2
	v_lshl_add_u64 v[186:187], v[182:183], 0, s[0:1]
	s_mov_b32 s71, 2
	s_mov_b64 s[64:65], 0
	s_mov_b32 s91, 64
	s_waitcnt vmcnt(3)
	ds_write_b128 v209, v[112:115] offset:17408
	s_waitcnt vmcnt(2)
	ds_write_b128 v209, v[116:119] offset:26112
	s_waitcnt vmcnt(1)
	ds_write_b128 v210, v[120:123] offset:55296
	s_waitcnt vmcnt(0)
	ds_write_b128 v211, v[124:127] offset:30720
	s_waitcnt lgkmcnt(0)
	s_barrier
	s_branch .LBB0_297

; #define LAS __attribute__((address_space(3)))
; #define MFMA32(a, b, c) __builtin_amdgcn_mfma_f32_32x32x16_bf16((a), (b), (c), 0, 0, 0)
; #define VFRAG(ptr, off0, STR) ({ const s16x4 lo_ = vtr((ptr) + (off0)); const s16x4 hi_ = vtr((ptr) + (off0) + 8 * (STR)); (bf16x8){lo_[0], lo_[1], lo_[2], lo_[3], hi_[0], hi_[1], hi_[2], hi_[3]}; })
; __device__ __forceinline__ void diff_unit(const Frame& F, int b, int h, int qi, float lam, int dry) {
;     ...
;             const LAS unsigned char* kb = lds + kra + (it & 1) * DK_BUF;
;             const LAS unsigned char* vb = lds + vra + (it & 1) * DV_BUF;
;             f32x16 s0, s1;
; #pragma unroll
;             for (int r = 0; r < 16; ++r) { s0[r] = 0.f; s1[r] = 0.f; }
;             bf16x8 vpre0 = VFRAG(vb, 0, DV_STR), vpre1 = VFRAG(vb, 64, DV_STR), vpre2 = VFRAG(vb, 128, DV_STR), vpre3 = VFRAG(vb, 192, DV_STR);
;             bf16x8 vprf0 = VFRAG(vb, 16 * DV_STR, DV_STR), vprf1 = VFRAG(vb, 16 * DV_STR + 64, DV_STR);
;             __builtin_amdgcn_s_setprio(1);
; #pragma unroll
;             for (int ks = 0; ks < 4; ++ks) { const bf16x8 k0 = *(const LAS bf16x8*)(kb + ks * 32); s0 = MFMA32(k0, qf[ks], s0); }
;             if (!meta) {
; #pragma unroll
;                 for (int ks = 0; ks < 4; ++ks) { const bf16x8 k1 = *(const LAS bf16x8*)(kb + 32 * DK_STR + ks * 32); s1 = MFMA32(k1, qf[ks], s1); }
;             }
;             __builtin_amdgcn_s_setprio(0);
;             if (meta) {
; #pragma unroll
;                 for (int r = 8; r < 16; ++r) s0[r] = -INFINITY;
; #pragma unroll
;                 for (int r = 0; r < 16; ++r) s1[r] = -INFINITY;
;             } else if (key0 + 63 > tqw) {
; #pragma unroll
;                 for (int r = 0; r < 16; ++r) { const int c = (r & 3) + 8 * (r >> 2), lim = tq - key0 - 4 * hi; if (c > lim) s0[r] = -INFINITY; if (c + 32 > lim) s1[r] = -INFINITY; }
;             }
.LBB0_301:
	s_add_i32 s0, s71, -1
	s_and_b32 s0, s0, 1
	s_mul_i32 s1, s0, 0x5000
	s_mulk_i32 s0, 0x4400
	v_add_u32_e32 v223, s0, v212
	v_add_u32_e32 v222, s1, v213
	ds_read_b128 v[64:67], v223
	ds_read_b128 v[68:71], v223 offset:32
	ds_read_b64_tr_b16 v[148:149], v222 offset:34816
	ds_read_b64_tr_b16 v[144:145], v222 offset:34880
	ds_read_b64_tr_b16 v[140:141], v222 offset:34944
	ds_read_b64_tr_b16 v[136:137], v222 offset:35008
	ds_read_b64_tr_b16 v[150:151], v222 offset:37376
	ds_read_b64_tr_b16 v[146:147], v222 offset:37440
	ds_read_b64_tr_b16 v[142:143], v222 offset:37504
	ds_read_b64_tr_b16 v[138:139], v222 offset:37568
	ds_read_b64_tr_b16 v[128:129], v222 offset:39936
	ds_read_b64_tr_b16 v[130:131], v222 offset:42496
	ds_read_b64_tr_b16 v[134:135], v222 offset:42560
	ds_read_b64_tr_b16 v[132:133], v222 offset:40000
	s_setprio 1
	s_waitcnt lgkmcnt(13)
	v_mfma_f32_32x32x16_bf16 v[80:95], v[64:67], v[96:99], v[238:253]
	s_waitcnt lgkmcnt(12)
	v_mfma_f32_32x32x16_bf16 v[80:95], v[68:71], v[100:103], v[80:95]
	ds_read_b128 v[64:67], v223 offset:64
	ds_read_b128 v[68:71], v223 offset:96
	s_waitcnt lgkmcnt(1)
	v_mfma_f32_32x32x16_bf16 v[80:95], v[64:67], v[104:107], v[80:95]
	ds_read_b128 v[64:67], v223 offset:8704
	ds_read_b128 v[224:227], v223 offset:8736
	s_waitcnt lgkmcnt(2)
	v_mfma_f32_32x32x16_bf16 v[80:95], v[68:71], v[108:111], v[80:95]
	s_waitcnt lgkmcnt(1)
	v_mfma_f32_32x32x16_bf16 v[64:79], v[64:67], v[96:99], v[238:253]
	s_waitcnt lgkmcnt(0)
	v_mfma_f32_32x32x16_bf16 v[64:79], v[224:227], v[100:103], v[64:79]
	ds_read_b128 v[224:227], v223 offset:8768
	ds_read_b128 v[228:231], v223 offset:8800
	s_waitcnt lgkmcnt(1)
	v_mfma_f32_32x32x16_bf16 v[64:79], v[224:227], v[104:107], v[64:79]
	s_waitcnt lgkmcnt(0)
	v_mfma_f32_32x32x16_bf16 v[64:79], v[228:231], v[108:111], v[64:79]
	s_setprio 0
	s_cmp_le_u32 s91, s10
	s_cbranch_scc1 .LBB0_303
	v_cmp_gt_i32_e64 s[60:61], s80, v153
	v_cmp_gt_i32_e64 s[62:63], s81, v153
	v_cmp_gt_i32_e64 s[58:59], s69, v153
	s_and_b64 s[60:61], s[62:63], s[60:61]
	v_cmp_gt_i32_e64 s[56:57], s68, v153
	s_and_b64 s[58:59], s[60:61], s[58:59]
	v_cmp_gt_i32_e64 s[54:55], s87, v153
	s_and_b64 s[56:57], s[58:59], s[56:57]
	v_cmp_gt_i32_e64 s[52:53], s86, v153
	s_and_b64 s[54:55], s[56:57], s[54:55]
	v_cmp_gt_i32_e64 s[50:51], s85, v153
	s_and_b64 s[52:53], s[54:55], s[52:53]
	v_cmp_gt_i32_e64 s[48:49], s79, v153
	s_and_b64 s[50:51], s[52:53], s[50:51]
	v_cmp_gt_i32_e64 s[46:47], s78, v153
	s_and_b64 s[48:49], s[50:51], s[48:49]
	v_cmp_gt_i32_e64 s[44:45], s77, v153
	s_and_b64 s[46:47], s[48:49], s[46:47]
	v_cmp_gt_i32_e64 s[42:43], s76, v153
	s_and_b64 s[44:45], s[46:47], s[44:45]
	v_cmp_gt_i32_e64 s[40:41], s96, v153
	s_and_b64 s[42:43], s[44:45], s[42:43]
	v_cmp_gt_i32_e64 s[38:39], s97, v153
	s_and_b64 s[40:41], s[42:43], s[40:41]
	v_cmp_gt_i32_e64 s[36:37], s93, v153
	s_and_b64 s[38:39], s[40:41], s[38:39]
	v_cmp_gt_i32_e64 s[34:35], s92, v153
	s_and_b64 s[36:37], s[38:39], s[36:37]
	v_cmp_gt_i32_e64 s[30:31], s11, v153
	s_and_b64 s[34:35], s[36:37], s[34:35]
	s_and_b64 s[30:31], s[34:35], s[30:31]
	v_cmp_gt_i32_e64 s[28:29], 10, v153
	v_cndmask_b32_e64 v80, v80, v221, s[30:31]
	v_cmp_gt_i32_e64 s[30:31], 11, v153
	v_cmp_gt_i32_e64 s[26:27], 9, v153
	s_and_b64 s[28:29], s[30:31], s[28:29]
	v_cmp_gt_i32_e64 s[24:25], 8, v153
	s_and_b64 s[26:27], s[28:29], s[26:27]
	v_cmp_gt_i32_e64 s[22:23], 3, v153
	s_and_b64 s[24:25], s[26:27], s[24:25]
	v_cmp_gt_i32_e64 s[20:21], 2, v153
	s_and_b64 s[22:23], s[24:25], s[22:23]
	v_cmp_gt_i32_e64 s[18:19], 1, v153
	s_and_b64 s[20:21], s[22:23], s[20:21]
	v_cmp_lt_u32_e64 s[16:17], s84, v153
	s_and_b64 s[18:19], s[20:21], s[18:19]
	v_cmp_gt_i32_e64 s[14:15], -5, v153
	s_and_b64 s[16:17], s[18:19], s[16:17]
	v_cmp_gt_i32_e64 s[12:13], -6, v153
	s_and_b64 s[14:15], s[16:17], s[14:15]
	v_cmp_gt_i32_e64 s[8:9], -7, v153
	s_and_b64 s[12:13], s[14:15], s[12:13]
	v_cmp_gt_i32_e64 s[6:7], -8, v153
	s_and_b64 s[8:9], s[12:13], s[8:9]
	v_cmp_gt_i32_e64 s[4:5], -13, v153
	s_and_b64 s[6:7], s[8:9], s[6:7]
	v_cmp_gt_i32_e64 s[2:3], -14, v153
	s_and_b64 s[4:5], s[6:7], s[4:5]
	v_cmp_gt_i32_e64 s[0:1], -15, v153
	s_and_b64 s[2:3], s[4:5], s[2:3]
	v_cmp_gt_i32_e32 vcc, -16, v153
	s_and_b64 s[0:1], s[2:3], s[0:1]
	s_and_b64 vcc, s[0:1], vcc
	v_cndmask_b32_e64 v95, v95, v221, s[62:63]
	v_cndmask_b32_e64 v94, v94, v221, s[60:61]
	v_cndmask_b32_e64 v93, v93, v221, s[58:59]
	v_cndmask_b32_e64 v92, v92, v221, s[56:57]
	v_cndmask_b32_e64 v91, v91, v221, s[54:55]
	v_cndmask_b32_e64 v90, v90, v221, s[52:53]
	v_cndmask_b32_e64 v89, v89, v221, s[50:51]
	v_cndmask_b32_e64 v88, v88, v221, s[48:49]
	v_cndmask_b32_e64 v87, v87, v221, s[46:47]
	v_cndmask_b32_e64 v86, v86, v221, s[44:45]
	v_cndmask_b32_e64 v85, v85, v221, s[42:43]
	v_cndmask_b32_e64 v84, v84, v221, s[40:41]
	v_cndmask_b32_e64 v83, v83, v221, s[38:39]
	v_cndmask_b32_e64 v82, v82, v221, s[36:37]
	v_cndmask_b32_e64 v81, v81, v221, s[34:35]
	v_cndmask_b32_e64 v79, v79, v221, s[30:31]
	v_cndmask_b32_e64 v78, v78, v221, s[28:29]
	v_cndmask_b32_e64 v77, v77, v221, s[26:27]
	v_cndmask_b32_e64 v76, v76, v221, s[24:25]
	v_cndmask_b32_e64 v75, v75, v221, s[22:23]
	v_cndmask_b32_e64 v74, v74, v221, s[20:21]
	v_cndmask_b32_e64 v73, v73, v221, s[18:19]
	v_cndmask_b32_e64 v72, v72, v221, s[16:17]
	v_cndmask_b32_e64 v71, v71, v221, s[14:15]
	v_cndmask_b32_e64 v70, v70, v221, s[12:13]
	v_cndmask_b32_e64 v69, v69, v221, s[8:9]
	v_cndmask_b32_e64 v68, v68, v221, s[6:7]
	v_cndmask_b32_e64 v67, v67, v221, s[4:5]
	v_cndmask_b32_e64 v66, v66, v221, s[2:3]
	v_cndmask_b32_e64 v65, v65, v221, s[0:1]
	v_cndmask_b32_e32 v64, v64, v221, vcc
; __device__ __forceinline__ void diff_unit(const Frame& F, int b, int h, int qi, float lam, int dry) {
;     ...
;             float mx = fmaxf(s0[0], s1[0]);
; #pragma unroll
;             for (int r = 1; r < 16; ++r) mx = fmaxf(mx, fmaxf(s0[r], s1[r]));
;             mx = fmaxf(mx, __shfl_xor(mx, 32));
;             const float mxs = mx * LOG2E;
;             if (__any(mxs > ms + 8.0f)) {
;                 const float msn = fmaxf(ms, mxs); const float f = __builtin_amdgcn_exp2f(ms - msn); lsum *= f; ms = msn;
; #pragma unroll
;                 for (int dt = 0; dt < 4; ++dt)
; #pragma unroll
;                     for (int r = 0; r < 16; ++r) O[dt][r] *= f;
;             }
.LBB0_303:
	v_max3_f32 v223, v80, v81, v82
	v_max3_f32 v223, v223, v83, v84
	v_max3_f32 v223, v223, v85, v86
	v_max3_f32 v223, v223, v87, v88
	v_max3_f32 v223, v223, v89, v90
	v_max3_f32 v223, v223, v91, v92
	v_max3_f32 v223, v223, v93, v94
	s_nop 2
	v_max3_f32 v224, v64, v65, v66
	v_max3_f32 v224, v224, v67, v68
	v_max3_f32 v224, v224, v69, v70
	v_max3_f32 v224, v224, v71, v72
	v_max3_f32 v224, v224, v73, v74
	v_max3_f32 v224, v224, v75, v76
	v_max3_f32 v224, v224, v77, v78
	v_max3_f32 v223, v223, v224, v95
	v_max_f32_e32 v223, v223, v79
	v_mov_b32_e32 v224, v223
	s_nop 1
	v_permlane32_swap_b32_e32 v223, v224
	v_max_f32_e32 v223, v223, v224
	v_cmp_lt_f32_e32 vcc, 0x41000000, v223
	s_cbranch_vccz .LBB0_305
	v_max_f32_e32 v223, 0, v223
	v_exp_f32_e64 v224, -v223
	v_add_f32_e32 v185, v185, v223
	v_pk_mul_f32 v[62:63], v[62:63], v[224:225] op_sel_hi:[1,0]
	v_pk_mul_f32 v[60:61], v[60:61], v[224:225] op_sel_hi:[1,0]
	v_pk_mul_f32 v[58:59], v[58:59], v[224:225] op_sel_hi:[1,0]
	v_pk_mul_f32 v[56:57], v[56:57], v[224:225] op_sel_hi:[1,0]
	v_pk_mul_f32 v[54:55], v[54:55], v[224:225] op_sel_hi:[1,0]
	v_pk_mul_f32 v[52:53], v[52:53], v[224:225] op_sel_hi:[1,0]
	v_pk_mul_f32 v[50:51], v[50:51], v[224:225] op_sel_hi:[1,0]
	v_pk_mul_f32 v[48:49], v[48:49], v[224:225] op_sel_hi:[1,0]
	v_pk_mul_f32 v[46:47], v[46:47], v[224:225] op_sel_hi:[1,0]
	v_pk_mul_f32 v[44:45], v[44:45], v[224:225] op_sel_hi:[1,0]
	v_pk_mul_f32 v[42:43], v[42:43], v[224:225] op_sel_hi:[1,0]
	v_pk_mul_f32 v[40:41], v[40:41], v[224:225] op_sel_hi:[1,0]
	v_pk_mul_f32 v[38:39], v[38:39], v[224:225] op_sel_hi:[1,0]
	v_pk_mul_f32 v[36:37], v[36:37], v[224:225] op_sel_hi:[1,0]
	v_pk_mul_f32 v[34:35], v[34:35], v[224:225] op_sel_hi:[1,0]
	v_pk_mul_f32 v[32:33], v[32:33], v[224:225] op_sel_hi:[1,0]
	v_pk_mul_f32 v[30:31], v[30:31], v[224:225] op_sel_hi:[1,0]
	v_pk_mul_f32 v[28:29], v[28:29], v[224:225] op_sel_hi:[1,0]
	v_pk_mul_f32 v[26:27], v[26:27], v[224:225] op_sel_hi:[1,0]
	v_pk_mul_f32 v[24:25], v[24:25], v[224:225] op_sel_hi:[1,0]
	v_pk_mul_f32 v[22:23], v[22:23], v[224:225] op_sel_hi:[1,0]
	v_pk_mul_f32 v[20:21], v[20:21], v[224:225] op_sel_hi:[1,0]
	v_pk_mul_f32 v[18:19], v[18:19], v[224:225] op_sel_hi:[1,0]
	v_pk_mul_f32 v[16:17], v[16:17], v[224:225] op_sel_hi:[1,0]
	v_pk_mul_f32 v[14:15], v[14:15], v[224:225] op_sel_hi:[1,0]
	v_pk_mul_f32 v[12:13], v[12:13], v[224:225] op_sel_hi:[1,0]
	v_pk_mul_f32 v[10:11], v[10:11], v[224:225] op_sel_hi:[1,0]
	v_pk_mul_f32 v[8:9], v[8:9], v[224:225] op_sel_hi:[1,0]
	v_pk_mul_f32 v[6:7], v[6:7], v[224:225] op_sel_hi:[1,0]
	v_pk_mul_f32 v[4:5], v[4:5], v[224:225] op_sel_hi:[1,0]
	v_pk_mul_f32 v[2:3], v[2:3], v[224:225] op_sel_hi:[1,0]
	v_pk_mul_f32 v[0:1], v[0:1], v[224:225] op_sel_hi:[1,0]
	v_mul_f32_e32 v158, v158, v224
	v_sub_f32_e32 v64, v64, v223
	v_sub_f32_e32 v65, v65, v223
	v_sub_f32_e32 v66, v66, v223
	v_sub_f32_e32 v67, v67, v223
	v_sub_f32_e32 v68, v68, v223
	v_sub_f32_e32 v69, v69, v223
	v_sub_f32_e32 v70, v70, v223
	v_sub_f32_e32 v71, v71, v223
	v_sub_f32_e32 v72, v72, v223
	v_sub_f32_e32 v73, v73, v223
	v_sub_f32_e32 v74, v74, v223
	v_sub_f32_e32 v75, v75, v223
	v_sub_f32_e32 v76, v76, v223
	v_sub_f32_e32 v77, v77, v223
	v_sub_f32_e32 v78, v78, v223
	v_sub_f32_e32 v79, v79, v223
	v_sub_f32_e32 v80, v80, v223
	v_sub_f32_e32 v81, v81, v223
	v_sub_f32_e32 v82, v82, v223
	v_sub_f32_e32 v83, v83, v223
	v_sub_f32_e32 v84, v84, v223
	v_sub_f32_e32 v85, v85, v223
	v_sub_f32_e32 v86, v86, v223
	v_sub_f32_e32 v87, v87, v223
	v_sub_f32_e32 v88, v88, v223
	v_sub_f32_e32 v89, v89, v223
	v_sub_f32_e32 v90, v90, v223
	v_sub_f32_e32 v91, v91, v223
	v_sub_f32_e32 v92, v92, v223
	v_sub_f32_e32 v93, v93, v223
	v_sub_f32_e32 v94, v94, v223
	v_sub_f32_e32 v95, v95, v223
	v_sub_f32_e32 v238, v238, v223
	v_sub_f32_e32 v239, v239, v223
	v_sub_f32_e32 v240, v240, v223
	v_sub_f32_e32 v241, v241, v223
	v_sub_f32_e32 v242, v242, v223
	v_sub_f32_e32 v243, v243, v223
	v_sub_f32_e32 v244, v244, v223
	v_sub_f32_e32 v245, v245, v223
	v_sub_f32_e32 v246, v246, v223
	v_sub_f32_e32 v247, v247, v223
	v_sub_f32_e32 v248, v248, v223
	v_sub_f32_e32 v249, v249, v223
	v_sub_f32_e32 v250, v250, v223
	v_sub_f32_e32 v251, v251, v223
	v_sub_f32_e32 v252, v252, v223
	v_sub_f32_e32 v253, v253, v223
; #define MFMA32(a, b, c) __builtin_amdgcn_mfma_f32_32x32x16_bf16((a), (b), (c), 0, 0, 0)
; #define VFRAG(ptr, off0, STR) ({ const s16x4 lo_ = vtr((ptr) + (off0)); const s16x4 hi_ = vtr((ptr) + (off0) + 8 * (STR)); (bf16x8){lo_[0], lo_[1], lo_[2], lo_[3], hi_[0], hi_[1], hi_[2], hi_[3]}; })
; __device__ __forceinline__ void diff_unit(const Frame& F, int b, int h, int qi, float lam, int dry) {
;     ...
;             float ps = 0.f;
; #pragma unroll
;             for (int r = 0; r < 16; ++r) { s0[r] = __builtin_amdgcn_exp2f(s0[r] * LOG2E - ms); ps += s0[r]; }
;             if (!meta) {
; #pragma unroll
;                 for (int r = 0; r < 16; ++r) { s1[r] = __builtin_amdgcn_exp2f(s1[r] * LOG2E - ms); ps += s1[r]; }
;             }
;             lsum += ps;
;             __builtin_amdgcn_s_setprio(1);
;             { const bf16x8 pf = pack_step(s0, 0);
;               O[0] = MFMA32(vpre0, pf, O[0]); O[1] = MFMA32(vpre1, pf, O[1]); O[2] = MFMA32(vpre2, pf, O[2]); O[3] = MFMA32(vpre3, pf, O[3]); }
;             if (!meta) {
;                 { const bf16x8 pf = pack_step(s0, 1);
;                   O[0] = MFMA32(vprf0, pf, O[0]); O[1] = MFMA32(vprf1, pf, O[1]);
; #pragma unroll
;                   for (int dt = 2; dt < 4; ++dt) { const bf16x8 vf = VFRAG(vb, 16 * DV_STR + 64 * dt, DV_STR); O[dt] = MFMA32(vf, pf, O[dt]); } }
; #pragma unroll
;                 for (int s2 = 0; s2 < 2; ++s2) { const bf16x8 pf = pack_step(s1, s2);
; #pragma unroll
;                     for (int dt = 0; dt < 4; ++dt) { const bf16x8 vf = VFRAG(vb, (32 + 16 * s2) * DV_STR + 64 * dt, DV_STR); O[dt] = MFMA32(vf, pf, O[dt]); } }
;             }
;             __builtin_amdgcn_s_setprio(0);
.LBB0_305:
	ds_read_b64_tr_b16 v[224:225], v222 offset:40064
	ds_read_b64_tr_b16 v[226:227], v222 offset:42624
	ds_read_b64_tr_b16 v[228:229], v222 offset:40128
	ds_read_b64_tr_b16 v[230:231], v222 offset:42688
	v_exp_f32_e32 v80, v80
	v_exp_f32_e32 v81, v81
	v_exp_f32_e32 v82, v82
	v_exp_f32_e32 v83, v83
	v_exp_f32_e32 v84, v84
	v_exp_f32_e32 v85, v85
	v_exp_f32_e32 v86, v86
	v_exp_f32_e32 v87, v87
	v_add_f32_e32 v236, v80, v82
	v_add_f32_e32 v237, v81, v83
	s_setprio 1
	v_cvt_pk_bf16_f32 v232, v80, v81
	v_cvt_pk_bf16_f32 v233, v82, v83
	v_cvt_pk_bf16_f32 v234, v84, v85
	v_cvt_pk_bf16_f32 v235, v86, v87
	v_add_f32_e32 v236, v236, v84
	v_add_f32_e32 v237, v237, v85
	v_add_f32_e32 v236, v236, v86
	v_add_f32_e32 v237, v237, v87
	v_mfma_f32_32x32x16_bf16 v[48:63], v[148:151], v[232:235], v[48:63]
	ds_read_b64_tr_b16 v[148:149], v222 offset:45056
	ds_read_b64_tr_b16 v[150:151], v222 offset:47616
	v_exp_f32_e32 v88, v88
	v_exp_f32_e32 v89, v89
	v_mfma_f32_32x32x16_bf16 v[32:47], v[144:147], v[232:235], v[32:47]
	ds_read_b64_tr_b16 v[144:145], v222 offset:45120
	ds_read_b64_tr_b16 v[146:147], v222 offset:47680
	v_exp_f32_e32 v90, v90
	v_exp_f32_e32 v91, v91
	v_add_f32_e32 v236, v236, v88
	v_add_f32_e32 v237, v237, v89
	v_cvt_pk_bf16_f32 v80, v88, v89
	v_mfma_f32_32x32x16_bf16 v[16:31], v[140:143], v[232:235], v[16:31]
	ds_read_b64_tr_b16 v[140:141], v222 offset:45184
	ds_read_b64_tr_b16 v[142:143], v222 offset:47744
	v_exp_f32_e32 v92, v92
	v_exp_f32_e32 v93, v93
	v_add_f32_e32 v236, v236, v90
	v_add_f32_e32 v237, v237, v91
	v_cvt_pk_bf16_f32 v81, v90, v91
	v_mfma_f32_32x32x16_bf16 v[0:15], v[136:139], v[232:235], v[0:15]
	ds_read_b64_tr_b16 v[136:137], v222 offset:45248
	ds_read_b64_tr_b16 v[138:139], v222 offset:47808
	v_exp_f32_e32 v94, v94
	v_exp_f32_e32 v95, v95
	v_add_f32_e32 v236, v236, v92
	v_add_f32_e32 v237, v237, v93
	v_cvt_pk_bf16_f32 v82, v92, v93
	v_cvt_pk_bf16_f32 v83, v94, v95
	v_add_f32_e32 v236, v236, v94
	v_add_f32_e32 v237, v237, v95
	s_nop 0
	v_mfma_f32_32x32x16_bf16 v[48:63], v[128:131], v[80:83], v[48:63]
	ds_read_b64_tr_b16 v[128:129], v222 offset:50176
	ds_read_b64_tr_b16 v[130:131], v222 offset:52736
	v_exp_f32_e32 v64, v64
	v_exp_f32_e32 v65, v65
	v_mfma_f32_32x32x16_bf16 v[32:47], v[132:135], v[80:83], v[32:47]
	ds_read_b64_tr_b16 v[132:133], v222 offset:50240
	ds_read_b64_tr_b16 v[134:135], v222 offset:52800
	v_exp_f32_e32 v66, v66
	v_exp_f32_e32 v67, v67
	v_add_f32_e32 v236, v236, v64
	v_add_f32_e32 v237, v237, v65
	v_cvt_pk_bf16_f32 v84, v64, v65
	s_waitcnt lgkmcnt(14)
	v_mfma_f32_32x32x16_bf16 v[16:31], v[224:227], v[80:83], v[16:31]
	ds_read_b64_tr_b16 v[224:225], v222 offset:50304
	ds_read_b64_tr_b16 v[226:227], v222 offset:52864
	v_exp_f32_e32 v68, v68
	v_exp_f32_e32 v69, v69
	v_add_f32_e32 v236, v236, v66
	v_add_f32_e32 v237, v237, v67
	v_cvt_pk_bf16_f32 v85, v66, v67
	s_waitcnt lgkmcnt(14)
	v_mfma_f32_32x32x16_bf16 v[0:15], v[228:231], v[80:83], v[0:15]
	ds_read_b64_tr_b16 v[228:229], v222 offset:50368
	ds_read_b64_tr_b16 v[230:231], v222 offset:52928
	v_exp_f32_e32 v70, v70
	v_exp_f32_e32 v71, v71
	v_add_f32_e32 v236, v236, v68
	v_add_f32_e32 v237, v237, v69
	v_cvt_pk_bf16_f32 v86, v68, v69
	v_cvt_pk_bf16_f32 v87, v70, v71
	v_add_f32_e32 v236, v236, v70
	v_add_f32_e32 v237, v237, v71
	s_nop 0
	s_waitcnt lgkmcnt(14)
	v_mfma_f32_32x32x16_bf16 v[48:63], v[148:151], v[84:87], v[48:63]
	v_exp_f32_e32 v72, v72
	v_exp_f32_e32 v73, v73
	s_waitcnt lgkmcnt(12)
	v_mfma_f32_32x32x16_bf16 v[32:47], v[144:147], v[84:87], v[32:47]
	v_exp_f32_e32 v74, v74
	v_exp_f32_e32 v75, v75
	v_add_f32_e32 v236, v236, v72
	v_add_f32_e32 v237, v237, v73
	v_cvt_pk_bf16_f32 v232, v72, v73
	s_waitcnt lgkmcnt(10)
	v_mfma_f32_32x32x16_bf16 v[16:31], v[140:143], v[84:87], v[16:31]
	v_exp_f32_e32 v76, v76
	v_exp_f32_e32 v77, v77
	v_add_f32_e32 v236, v236, v74
	v_add_f32_e32 v237, v237, v75
	v_cvt_pk_bf16_f32 v233, v74, v75
	s_waitcnt lgkmcnt(8)
	v_mfma_f32_32x32x16_bf16 v[0:15], v[136:139], v[84:87], v[0:15]
	v_exp_f32_e32 v78, v78
	v_exp_f32_e32 v79, v79
	v_add_f32_e32 v236, v236, v76
	v_add_f32_e32 v237, v237, v77
	v_cvt_pk_bf16_f32 v234, v76, v77
	v_cvt_pk_bf16_f32 v235, v78, v79
	v_add_f32_e32 v236, v236, v78
	v_add_f32_e32 v237, v237, v79
	v_add_f32_e32 v223, v236, v237
	v_add_f32_e32 v158, v158, v223
	s_waitcnt lgkmcnt(6)
	v_mfma_f32_32x32x16_bf16 v[48:63], v[128:131], v[232:235], v[48:63]
	s_waitcnt lgkmcnt(4)
	v_mfma_f32_32x32x16_bf16 v[32:47], v[132:135], v[232:235], v[32:47]
	s_waitcnt lgkmcnt(2)
	v_mfma_f32_32x32x16_bf16 v[16:31], v[224:227], v[232:235], v[16:31]
	s_waitcnt lgkmcnt(0)
	v_mfma_f32_32x32x16_bf16 v[0:15], v[228:231], v[232:235], v[0:15]
	s_setprio 0
	s_andn2_b64 vcc, exec, s[66:67]
	s_cbranch_vccnz .LBB0_296

; __device__ __forceinline__ void diff_unit(const Frame& F, int b, int h, int qi, float lam, int dry) {
;     ...
;     bf16* QA = (bf16*)(F.ws + WS_SEC); const bf16* KA = QA + SEC_ELEMS; const bf16* VA = QA + 2 * SEC_ELEMS;
;     bf16x8 qf[4];
;     { const bf16* qp = QA + (rowbase + tq) * 1024 + 128 * h + 64 * map + 8 * hi;
; #pragma unroll
;       for (int ks = 0; ks < 4; ++ks) qf[ks] = *(const bf16x8*)(qp + 16 * ks); }
;     const int srow = tid >> 4, sc16 = tid & 15;
;     const bf16* kg = KA + (rowbase + srow) * 1024 + 128 * h + sc16 * 8;
;     const bf16* vg = VA + (rowbase + srow) * 1024 + 128 * h + sc16 * 8;
;     const int klds = D_KOFF + srow * DK_STR + sc16 * 16, vlds = D_VOFF + srow * DV_STR + sc16 * 16;
;     u32x4 st0, st1, st2, st3;
;     ...
;     const int nt = 2 * qi + 3;
;     __syncthreads();
;     D_LOAD(0); D_STORE(0);
;     __syncthreads();
;     f32x16 O[4];
; #pragma unroll
;     for (int dt = 0; dt < 4; ++dt)
; #pragma unroll
;         for (int r = 0; r < 16; ++r) O[dt][r] = 0.f;
;     float ms = -INFINITY, lsum = 0.f;
;     const int kra = D_KOFF + r32 * DK_STR + map * 128 + hi * 16;
;     const int vra = D_VOFF + (4 * hi + ((lane & 15) >> 2)) * DV_STR + (16 * ((lane >> 4) & 1) + 4 * (lane & 3)) * 2;
;     for (int it = 0; it < nt; ++it) {
;         const int key0 = it == 0 ? 0 : NMETA + 64 * (it - 1);
;         if (it + 1 < nt) D_LOAD(NMETA + 64 * it);
;         const bool meta = (it == 0);
;         if (meta || key0 <= tqw + 31) {
;             const LAS unsigned char* kb = lds + kra + (it & 1) * DK_BUF;
;             const LAS unsigned char* vb = lds + vra + (it & 1) * DV_BUF;
;             f32x16 s0, s1;
; #pragma unroll
;             for (int r = 0; r < 16; ++r) { s0[r] = 0.f; s1[r] = 0.f; }
;             bf16x8 vpre0 = VFRAG(vb, 0, DV_STR), vpre1 = VFRAG(vb, 64, DV_STR), vpre2 = VFRAG(vb, 128, DV_STR), vpre3 = VFRAG(vb, 192, DV_STR);
;             bf16x8 vprf0 = VFRAG(vb, 16 * DV_STR, DV_STR), vprf1 = VFRAG(vb, 16 * DV_STR + 64, DV_STR);
;             __builtin_amdgcn_s_setprio(1);
; #pragma unroll
;             for (int ks = 0; ks < 4; ++ks) { const bf16x8 k0 = *(const LAS bf16x8*)(kb + ks * 32); s0 = MFMA32(k0, qf[ks], s0); }
;             if (!meta) {
; #pragma unroll
;                 for (int ks = 0; ks < 4; ++ks) { const bf16x8 k1 = *(const LAS bf16x8*)(kb + 32 * DK_STR + ks * 32); s1 = MFMA32(k1, qf[ks], s1); }
;             }
.LBB0_311:
	s_xor_b32 s1, s90, 31
	s_lshl_b32 s0, s1, 7
	v_readlane_b32 s2, v254, 56
	s_or_b32 s71, s2, s0
	s_or_b32 s89, s71, 16
	v_add_u32_e32 v158, s89, v204
	v_lshl_add_u64 v[0:1], s[72:73], 0, v[158:159]
	v_readlane_b32 s2, v254, 32
	v_lshlrev_b64 v[0:1], 11, v[0:1]
	v_readlane_b32 s3, v254, 33
	s_mov_b32 s95, s75
	v_mov_b32_e32 v153, v159
	v_lshl_add_u64 v[0:1], s[2:3], 0, v[0:1]
	v_lshl_add_u64 v[0:1], v[0:1], 0, s[74:75]
	v_lshl_add_u64 v[0:1], v[0:1], 0, s[94:95]
	v_lshl_add_u64 v[0:1], v[0:1], 0, v[152:153]
	global_load_dwordx4 v[96:99], v[0:1], off
	global_load_dwordx4 v[100:103], v[0:1], off offset:32
	global_load_dwordx4 v[104:107], v[0:1], off offset:64
	global_load_dwordx4 v[108:111], v[0:1], off offset:96
	global_load_dwordx4 v[0:3], v[188:189], off
	global_load_dwordx4 v[4:7], v[200:201], off
	global_load_dwordx4 v[8:11], v[190:191], off
	global_load_dwordx4 v[12:15], v[202:203], off
	global_load_dwordx4 v[112:115], v[192:193], off
	global_load_dwordx4 v[116:119], v[194:195], off
	global_load_dwordx4 v[120:123], v[196:197], off
	global_load_dwordx4 v[124:127], v[198:199], off
	s_barrier
	s_waitcnt vmcnt(7)
	ds_write_b128 v209, v[0:3]
	s_waitcnt vmcnt(6)
	ds_write_b128 v209, v[4:7] offset:8704
	s_waitcnt vmcnt(5)
	ds_write_b128 v210, v[8:11] offset:34816
	s_waitcnt vmcnt(4)
	ds_write_b128 v210, v[12:15] offset:45056
	s_waitcnt lgkmcnt(0)
	s_barrier
	ds_read_b64_tr_b16 v[32:33], v213 offset:34816
	ds_read_b64_tr_b16 v[64:65], v213 offset:34880
	ds_read_b64_tr_b16 v[72:73], v213 offset:34944
	ds_read_b64_tr_b16 v[68:69], v213 offset:35008
	ds_read_b64_tr_b16 v[34:35], v213 offset:37376
	ds_read_b64_tr_b16 v[66:67], v213 offset:37440
	ds_read_b64_tr_b16 v[74:75], v213 offset:37504
	ds_read_b64_tr_b16 v[70:71], v213 offset:37568
	s_setprio 1
	ds_read_b128 v[0:3], v212
	ds_read_b128 v[4:7], v212 offset:32
	s_waitcnt lgkmcnt(1)
	v_mfma_f32_32x32x16_bf16 v[16:31], v[0:3], v[96:99], 0
	s_waitcnt lgkmcnt(0)
	v_mfma_f32_32x32x16_bf16 v[16:31], v[4:7], v[100:103], v[16:31]
	ds_read_b128 v[0:3], v212 offset:64
	ds_read_b128 v[4:7], v212 offset:96
	s_waitcnt lgkmcnt(1)
	v_mfma_f32_32x32x16_bf16 v[16:31], v[0:3], v[104:107], v[16:31]
	s_waitcnt lgkmcnt(0)
	v_mfma_f32_32x32x16_bf16 v[16:31], v[4:7], v[108:111], v[16:31]
	s_setprio 0
	s_nop 10
	v_max_f32_e32 v0, v16, v16
	v_max_f32_e32 v1, v17, v17
	v_max_f32_e32 v2, v18, v18
	v_max_f32_e32 v0, 0xff800000, v0
	v_max_f32_e32 v1, 0xff800000, v1
	v_max_f32_e32 v2, 0xff800000, v2
	v_max3_f32 v0, v0, v1, v2
	v_max_f32_e32 v1, v19, v19
	v_max_f32_e32 v2, v20, v20
	v_max_f32_e32 v1, 0xff800000, v1
	v_max_f32_e32 v2, 0xff800000, v2
	v_max3_f32 v0, v0, v1, v2
	v_max_f32_e32 v1, v21, v21
	v_max_f32_e32 v2, v22, v22
	v_max_f32_e32 v1, 0xff800000, v1
	v_max_f32_e32 v2, 0xff800000, v2
	v_max3_f32 v0, v0, v1, v2
	v_max_f32_e32 v1, v23, v23
	v_max_f32_e32 v1, 0xff800000, v1
	s_mov_b32 s2, 0xff800000
	v_max3_f32 v0, v0, v1, s2
	ds_bpermute_b32 v1, v155, v0
	s_waitcnt lgkmcnt(0)
	v_max_f32_e32 v1, v1, v1
	v_max_f32_e32 v0, v0, v1
	v_cmp_neq_f32_e32 vcc, s2, v0
	s_cbranch_vccz .LBB0_313
	v_max_f32_e32 v0, v0, v0
	v_max_f32_e32 v158, 0xff800000, v0
	v_sub_f32_e32 v0, 0xff800000, v158
	v_exp_f32_e32 v0, v0
	s_nop 0
	v_mul_f32_e32 v1, 0, v0
	v_mov_b32_e32 v0, v1
	s_branch .LBB0_314

; #define MFMA32(a, b, c) __builtin_amdgcn_mfma_f32_32x32x16_bf16((a), (b), (c), 0, 0, 0)
; #define VFRAG(ptr, off0, STR) ({ const s16x4 lo_ = vtr((ptr) + (off0)); const s16x4 hi_ = vtr((ptr) + (off0) + 8 * (STR)); (bf16x8){lo_[0], lo_[1], lo_[2], lo_[3], hi_[0], hi_[1], hi_[2], hi_[3]}; })
; #define D_STORE(buf) do { *(LAS u32x4*)(lds + klds + (buf) * DK_BUF) = st0; *(LAS u32x4*)(lds + klds + (buf) * DK_BUF + 32 * DK_STR) = st1; *(LAS u32x4*)(lds + vlds + (buf) * DV_BUF) = st2; *(LAS u32x4*)(lds + vlds + (buf) * DV_BUF + 32 * DV_STR) = st3; } while (0)
; __device__ __forceinline__ void diff_unit(const Frame& F, int b, int h, int qi, float lam, int dry) {
;     ...
;                 const float msn = fmaxf(ms, mxs); const float f = __builtin_amdgcn_exp2f(ms - msn); lsum *= f; ms = msn;
; #pragma unroll
;                 for (int dt = 0; dt < 4; ++dt)
; #pragma unroll
;                     for (int r = 0; r < 16; ++r) O[dt][r] *= f;
;             }
;             float ps = 0.f;
; #pragma unroll
;             for (int r = 0; r < 16; ++r) { s0[r] = __builtin_amdgcn_exp2f(s0[r] * LOG2E - ms); ps += s0[r]; }
;             if (!meta) {
; #pragma unroll
;                 for (int r = 0; r < 16; ++r) { s1[r] = __builtin_amdgcn_exp2f(s1[r] * LOG2E - ms); ps += s1[r]; }
;             }
;             lsum += ps;
;             __builtin_amdgcn_s_setprio(1);
;             { const bf16x8 pf = pack_step(s0, 0);
;               O[0] = MFMA32(vpre0, pf, O[0]); O[1] = MFMA32(vpre1, pf, O[1]); O[2] = MFMA32(vpre2, pf, O[2]); O[3] = MFMA32(vpre3, pf, O[3]); }
;             if (!meta) {
;                 { const bf16x8 pf = pack_step(s0, 1);
;                   O[0] = MFMA32(vprf0, pf, O[0]); O[1] = MFMA32(vprf1, pf, O[1]);
; #pragma unroll
;                   for (int dt = 2; dt < 4; ++dt) { const bf16x8 vf = VFRAG(vb, 16 * DV_STR + 64 * dt, DV_STR); O[dt] = MFMA32(vf, pf, O[dt]); } }
; #pragma unroll
;                 for (int s2 = 0; s2 < 2; ++s2) { const bf16x8 pf = pack_step(s1, s2);
; #pragma unroll
;                     for (int dt = 0; dt < 4; ++dt) { const bf16x8 vf = VFRAG(vb, (32 + 16 * s2) * DV_STR + 64 * dt, DV_STR); O[dt] = MFMA32(vf, pf, O[dt]); } }
;             }
;             __builtin_amdgcn_s_setprio(0);
;         }
;         if (it + 1 < nt) D_STORE((it + 1) & 1);
.LBB0_314:
	v_sub_f32_e32 v238, 0, v158
	v_sub_f32_e32 v239, 0, v158
	v_sub_f32_e32 v240, 0, v158
	v_sub_f32_e32 v241, 0, v158
	v_sub_f32_e32 v242, 0, v158
	v_sub_f32_e32 v243, 0, v158
	v_sub_f32_e32 v244, 0, v158
	v_sub_f32_e32 v245, 0, v158
	v_sub_f32_e32 v246, 0, v158
	v_sub_f32_e32 v247, 0, v158
	v_sub_f32_e32 v248, 0, v158
	v_sub_f32_e32 v249, 0, v158
	v_sub_f32_e32 v250, 0, v158
	v_sub_f32_e32 v251, 0, v158
	v_sub_f32_e32 v252, 0, v158
	v_sub_f32_e32 v253, 0, v158
	v_sub_f32_e32 v16, v16, v158
	v_exp_f32_e32 v16, v16
	v_sub_f32_e32 v17, v17, v158
	v_exp_f32_e32 v17, v17
	v_sub_f32_e32 v18, v18, v158
	v_exp_f32_e32 v18, v18
	v_sub_f32_e32 v19, v19, v158
	v_exp_f32_e32 v19, v19
	v_sub_f32_e32 v20, v20, v158
	v_add_f32_e32 v24, 0, v16
	v_exp_f32_e32 v20, v20
	v_sub_f32_e32 v21, v21, v158
	v_add_f32_e32 v24, v17, v24
	v_exp_f32_e32 v21, v21
	v_sub_f32_e32 v22, v22, v158
	v_add_f32_e32 v24, v18, v24
	v_exp_f32_e32 v22, v22
	v_sub_f32_e32 v23, v23, v158
	v_add_f32_e32 v24, v19, v24
	v_exp_f32_e32 v23, v23
	v_sub_f32_e32 v25, 0xff800000, v158
	v_add_f32_e32 v24, v20, v24
	v_exp_f32_e32 v25, v25
	v_add_f32_e32 v24, v21, v24
	v_add_f32_e32 v24, v22, v24
	v_add_f32_e32 v24, v23, v24
	v_add_f32_e32 v24, v25, v24
	v_add_f32_e32 v24, v25, v24
	v_add_f32_e32 v24, v25, v24
	v_add_f32_e32 v24, v25, v24
	v_add_f32_e32 v24, v25, v24
	v_add_f32_e32 v24, v25, v24
	v_add_f32_e32 v24, v25, v24
	s_lshl_b32 s10, s1, 1
	v_add_f32_e32 v24, v25, v24
	v_mov_b32_e32 v2, v1
	v_mov_b32_e32 v3, v1
	v_mov_b32_e32 v4, v1
	v_mov_b32_e32 v5, v1
	v_mov_b32_e32 v6, v1
	v_mov_b32_e32 v7, v1
	v_mov_b32_e32 v8, v1
	v_mov_b32_e32 v9, v1
	v_mov_b32_e32 v10, v1
	v_mov_b32_e32 v11, v1
	v_mov_b32_e32 v12, v1
	v_mov_b32_e32 v13, v1
	v_mov_b32_e32 v14, v1
	v_mov_b32_e32 v15, v1
	s_add_i32 s10, s10, 3
	s_or_b32 s70, s71, 1
	s_addk_i32 s71, 0x5f
	v_add_f32_e32 v153, v1, v24
	s_setprio 1
	v_cvt_pk_bf16_f32 v76, v16, v17
	v_cvt_pk_bf16_f32 v77, v18, v19
	v_cvt_pk_bf16_f32 v78, v20, v21
	v_cvt_pk_bf16_f32 v79, v22, v23
	s_nop 1
	v_mfma_f32_32x32x16_bf16 v[48:63], v[32:35], v[76:79], v[0:15]
	v_mfma_f32_32x32x16_bf16 v[32:47], v[64:67], v[76:79], v[0:15]
	v_mfma_f32_32x32x16_bf16 v[16:31], v[72:75], v[76:79], v[0:15]
	v_mfma_f32_32x32x16_bf16 v[0:15], v[68:71], v[76:79], v[0:15]
	s_setprio 0
	s_lshl_b32 s1, s1, 18
	s_add_u32 s95, s1, 0x40000
	v_add_u32_e32 v185, s0, v217
	s_mov_b32 s2, 2
	s_mov_b64 s[66:67], 0
	s_mov_b32 s3, 64
	s_waitcnt vmcnt(3)
	ds_write_b128 v209, v[112:115] offset:17408
	s_waitcnt vmcnt(2)
	ds_write_b128 v209, v[116:119] offset:26112
	s_waitcnt vmcnt(1)
	ds_write_b128 v210, v[120:123] offset:55296
	s_waitcnt vmcnt(0)
	ds_write_b128 v211, v[124:127] offset:30720
	s_waitcnt lgkmcnt(0)
	s_barrier
	s_branch .LBB0_316

; #define LAS __attribute__((address_space(3)))
; #define MFMA32(a, b, c) __builtin_amdgcn_mfma_f32_32x32x16_bf16((a), (b), (c), 0, 0, 0)
; #define VFRAG(ptr, off0, STR) ({ const s16x4 lo_ = vtr((ptr) + (off0)); const s16x4 hi_ = vtr((ptr) + (off0) + 8 * (STR)); (bf16x8){lo_[0], lo_[1], lo_[2], lo_[3], hi_[0], hi_[1], hi_[2], hi_[3]}; })
; __device__ __forceinline__ void diff_unit(const Frame& F, int b, int h, int qi, float lam, int dry) {
;     ...
;             const LAS unsigned char* kb = lds + kra + (it & 1) * DK_BUF;
;             const LAS unsigned char* vb = lds + vra + (it & 1) * DV_BUF;
;             f32x16 s0, s1;
; #pragma unroll
;             for (int r = 0; r < 16; ++r) { s0[r] = 0.f; s1[r] = 0.f; }
;             bf16x8 vpre0 = VFRAG(vb, 0, DV_STR), vpre1 = VFRAG(vb, 64, DV_STR), vpre2 = VFRAG(vb, 128, DV_STR), vpre3 = VFRAG(vb, 192, DV_STR);
;             bf16x8 vprf0 = VFRAG(vb, 16 * DV_STR, DV_STR), vprf1 = VFRAG(vb, 16 * DV_STR + 64, DV_STR);
;             __builtin_amdgcn_s_setprio(1);
; #pragma unroll
;             for (int ks = 0; ks < 4; ++ks) { const bf16x8 k0 = *(const LAS bf16x8*)(kb + ks * 32); s0 = MFMA32(k0, qf[ks], s0); }
;             if (!meta) {
; #pragma unroll
;                 for (int ks = 0; ks < 4; ++ks) { const bf16x8 k1 = *(const LAS bf16x8*)(kb + 32 * DK_STR + ks * 32); s1 = MFMA32(k1, qf[ks], s1); }
;             }
;             __builtin_amdgcn_s_setprio(0);
;             if (meta) {
; #pragma unroll
;                 for (int r = 8; r < 16; ++r) s0[r] = -INFINITY;
; #pragma unroll
;                 for (int r = 0; r < 16; ++r) s1[r] = -INFINITY;
;             } else if (key0 + 63 > tqw) {
; #pragma unroll
;                 for (int r = 0; r < 16; ++r) { const int c = (r & 3) + 8 * (r >> 2), lim = tq - key0 - 4 * hi; if (c > lim) s0[r] = -INFINITY; if (c + 32 > lim) s1[r] = -INFINITY; }
;             }
.LBB0_320:
	s_add_i32 s0, s2, -1
	s_and_b32 s0, s0, 1
	s_mul_i32 s1, s0, 0x5000
	s_mulk_i32 s0, 0x4400
	v_add_u32_e32 v189, s0, v212
	v_add_u32_e32 v188, s1, v213
	ds_read_b128 v[64:67], v189
	ds_read_b128 v[68:71], v189 offset:32
	ds_read_b64_tr_b16 v[148:149], v188 offset:34816
	ds_read_b64_tr_b16 v[144:145], v188 offset:34880
	ds_read_b64_tr_b16 v[140:141], v188 offset:34944
	ds_read_b64_tr_b16 v[136:137], v188 offset:35008
	ds_read_b64_tr_b16 v[150:151], v188 offset:37376
	ds_read_b64_tr_b16 v[146:147], v188 offset:37440
	ds_read_b64_tr_b16 v[142:143], v188 offset:37504
	ds_read_b64_tr_b16 v[138:139], v188 offset:37568
	ds_read_b64_tr_b16 v[128:129], v188 offset:39936
	ds_read_b64_tr_b16 v[130:131], v188 offset:42496
	ds_read_b64_tr_b16 v[134:135], v188 offset:42560
	ds_read_b64_tr_b16 v[132:133], v188 offset:40000
	s_setprio 1
	s_waitcnt lgkmcnt(13)
	v_mfma_f32_32x32x16_bf16 v[80:95], v[64:67], v[96:99], v[238:253]
	s_waitcnt lgkmcnt(12)
	v_mfma_f32_32x32x16_bf16 v[80:95], v[68:71], v[100:103], v[80:95]
	ds_read_b128 v[64:67], v189 offset:64
	ds_read_b128 v[68:71], v189 offset:96
	s_waitcnt lgkmcnt(1)
	v_mfma_f32_32x32x16_bf16 v[80:95], v[64:67], v[104:107], v[80:95]
	ds_read_b128 v[64:67], v189 offset:8704
	ds_read_b128 v[190:193], v189 offset:8736
	s_waitcnt lgkmcnt(2)
	v_mfma_f32_32x32x16_bf16 v[80:95], v[68:71], v[108:111], v[80:95]
	s_waitcnt lgkmcnt(1)
	v_mfma_f32_32x32x16_bf16 v[64:79], v[64:67], v[96:99], v[238:253]
	s_waitcnt lgkmcnt(0)
	v_mfma_f32_32x32x16_bf16 v[64:79], v[190:193], v[100:103], v[64:79]
	ds_read_b128 v[190:193], v189 offset:8768
	ds_read_b128 v[194:197], v189 offset:8800
	s_waitcnt lgkmcnt(1)
	v_mfma_f32_32x32x16_bf16 v[64:79], v[190:193], v[104:107], v[64:79]
	s_waitcnt lgkmcnt(0)
	v_mfma_f32_32x32x16_bf16 v[64:79], v[194:197], v[108:111], v[64:79]
	s_setprio 0
	s_cmp_le_u32 s3, s70
	s_cbranch_scc1 .LBB0_322
	v_cmp_gt_i32_e64 s[62:63], s80, v185
	v_cmp_gt_i32_e64 s[64:65], s81, v185
	v_cmp_gt_i32_e64 s[60:61], s69, v185
	s_and_b64 s[62:63], s[64:65], s[62:63]
	v_cmp_gt_i32_e64 s[58:59], s68, v185
	s_and_b64 s[60:61], s[62:63], s[60:61]
	v_cmp_gt_i32_e64 s[56:57], s87, v185
	s_and_b64 s[58:59], s[60:61], s[58:59]
	v_cmp_gt_i32_e64 s[54:55], s86, v185
	s_and_b64 s[56:57], s[58:59], s[56:57]
	v_cmp_gt_i32_e64 s[52:53], s85, v185
	s_and_b64 s[54:55], s[56:57], s[54:55]
	v_cmp_gt_i32_e64 s[50:51], s79, v185
	s_and_b64 s[52:53], s[54:55], s[52:53]
	v_cmp_gt_i32_e64 s[48:49], s78, v185
	s_and_b64 s[50:51], s[52:53], s[50:51]
	v_cmp_gt_i32_e64 s[46:47], s77, v185
	s_and_b64 s[48:49], s[50:51], s[48:49]
	v_cmp_gt_i32_e64 s[44:45], s76, v185
	s_and_b64 s[46:47], s[48:49], s[46:47]
	v_cmp_gt_i32_e64 s[42:43], s96, v185
	s_and_b64 s[44:45], s[46:47], s[44:45]
	v_cmp_gt_i32_e64 s[40:41], s97, v185
	s_and_b64 s[42:43], s[44:45], s[42:43]
	v_cmp_gt_i32_e64 s[38:39], s93, v185
	s_and_b64 s[40:41], s[42:43], s[40:41]
	v_cmp_gt_i32_e64 s[36:37], s92, v185
	s_and_b64 s[38:39], s[40:41], s[38:39]
	v_cmp_gt_i32_e64 s[34:35], s11, v185
	s_and_b64 s[36:37], s[38:39], s[36:37]
	s_and_b64 s[34:35], s[36:37], s[34:35]
	v_cmp_gt_i32_e64 s[30:31], 10, v185
	v_cndmask_b32_e64 v80, v80, v221, s[34:35]
	v_cmp_gt_i32_e64 s[34:35], 11, v185
	v_cmp_gt_i32_e64 s[28:29], 9, v185
	s_and_b64 s[30:31], s[34:35], s[30:31]
	v_cmp_gt_i32_e64 s[26:27], 8, v185
	s_and_b64 s[28:29], s[30:31], s[28:29]
	v_cmp_gt_i32_e64 s[24:25], 3, v185
	s_and_b64 s[26:27], s[28:29], s[26:27]
	v_cmp_gt_i32_e64 s[22:23], 2, v185
	s_and_b64 s[24:25], s[26:27], s[24:25]
	v_cmp_gt_i32_e64 s[20:21], 1, v185
	s_and_b64 s[22:23], s[24:25], s[22:23]
	v_cmp_lt_u32_e64 s[18:19], s84, v185
	s_and_b64 s[20:21], s[22:23], s[20:21]
	v_cmp_gt_i32_e64 s[16:17], -5, v185
	s_and_b64 s[18:19], s[20:21], s[18:19]
	v_cmp_gt_i32_e64 s[14:15], -6, v185
	s_and_b64 s[16:17], s[18:19], s[16:17]
	v_cmp_gt_i32_e64 s[12:13], -7, v185
	s_and_b64 s[14:15], s[16:17], s[14:15]
	v_cmp_gt_i32_e64 s[8:9], -8, v185
	s_and_b64 s[12:13], s[14:15], s[12:13]
	v_cmp_gt_i32_e64 s[6:7], -13, v185
	s_and_b64 s[8:9], s[12:13], s[8:9]
	v_cmp_gt_i32_e64 s[4:5], -14, v185
	s_and_b64 s[6:7], s[8:9], s[6:7]
	v_cmp_gt_i32_e64 s[0:1], -15, v185
	s_and_b64 s[4:5], s[6:7], s[4:5]
	v_cmp_gt_i32_e32 vcc, -16, v185
	s_and_b64 s[0:1], s[4:5], s[0:1]
	s_and_b64 vcc, s[0:1], vcc
	v_cndmask_b32_e64 v95, v95, v221, s[64:65]
	v_cndmask_b32_e64 v94, v94, v221, s[62:63]
	v_cndmask_b32_e64 v93, v93, v221, s[60:61]
	v_cndmask_b32_e64 v92, v92, v221, s[58:59]
	v_cndmask_b32_e64 v91, v91, v221, s[56:57]
	v_cndmask_b32_e64 v90, v90, v221, s[54:55]
	v_cndmask_b32_e64 v89, v89, v221, s[52:53]
	v_cndmask_b32_e64 v88, v88, v221, s[50:51]
	v_cndmask_b32_e64 v87, v87, v221, s[48:49]
	v_cndmask_b32_e64 v86, v86, v221, s[46:47]
	v_cndmask_b32_e64 v85, v85, v221, s[44:45]
	v_cndmask_b32_e64 v84, v84, v221, s[42:43]
	v_cndmask_b32_e64 v83, v83, v221, s[40:41]
	v_cndmask_b32_e64 v82, v82, v221, s[38:39]
	v_cndmask_b32_e64 v81, v81, v221, s[36:37]
	v_cndmask_b32_e64 v79, v79, v221, s[34:35]
	v_cndmask_b32_e64 v78, v78, v221, s[30:31]
	v_cndmask_b32_e64 v77, v77, v221, s[28:29]
	v_cndmask_b32_e64 v76, v76, v221, s[26:27]
	v_cndmask_b32_e64 v75, v75, v221, s[24:25]
	v_cndmask_b32_e64 v74, v74, v221, s[22:23]
	v_cndmask_b32_e64 v73, v73, v221, s[20:21]
	v_cndmask_b32_e64 v72, v72, v221, s[18:19]
	v_cndmask_b32_e64 v71, v71, v221, s[16:17]
	v_cndmask_b32_e64 v70, v70, v221, s[14:15]
	v_cndmask_b32_e64 v69, v69, v221, s[12:13]
	v_cndmask_b32_e64 v68, v68, v221, s[8:9]
	v_cndmask_b32_e64 v67, v67, v221, s[6:7]
	v_cndmask_b32_e64 v66, v66, v221, s[4:5]
	v_cndmask_b32_e64 v65, v65, v221, s[0:1]
	v_cndmask_b32_e32 v64, v64, v221, vcc
; __device__ __forceinline__ void diff_unit(const Frame& F, int b, int h, int qi, float lam, int dry) {
;     ...
;             float mx = fmaxf(s0[0], s1[0]);
; #pragma unroll
;             for (int r = 1; r < 16; ++r) mx = fmaxf(mx, fmaxf(s0[r], s1[r]));
;             mx = fmaxf(mx, __shfl_xor(mx, 32));
;             const float mxs = mx * LOG2E;
;             if (__any(mxs > ms + 8.0f)) {
;                 const float msn = fmaxf(ms, mxs); const float f = __builtin_amdgcn_exp2f(ms - msn); lsum *= f; ms = msn;
; #pragma unroll
;                 for (int dt = 0; dt < 4; ++dt)
; #pragma unroll
;                     for (int r = 0; r < 16; ++r) O[dt][r] *= f;
;             }
.LBB0_322:
	v_max3_f32 v189, v80, v81, v82
	v_max3_f32 v189, v189, v83, v84
	v_max3_f32 v189, v189, v85, v86
	v_max3_f32 v189, v189, v87, v88
	v_max3_f32 v189, v189, v89, v90
	v_max3_f32 v189, v189, v91, v92
	v_max3_f32 v189, v189, v93, v94
	s_nop 2
	v_max3_f32 v190, v64, v65, v66
	v_max3_f32 v190, v190, v67, v68
	v_max3_f32 v190, v190, v69, v70
	v_max3_f32 v190, v190, v71, v72
	v_max3_f32 v190, v190, v73, v74
	v_max3_f32 v190, v190, v75, v76
	v_max3_f32 v190, v190, v77, v78
	v_max3_f32 v189, v189, v190, v95
	v_max_f32_e32 v189, v189, v79
	v_mov_b32_e32 v190, v189
	s_nop 1
	v_permlane32_swap_b32_e32 v189, v190
	v_max_f32_e32 v189, v189, v190
	v_cmp_lt_f32_e32 vcc, 0x41000000, v189
	s_cbranch_vccz .LBB0_324
	v_max_f32_e32 v189, 0, v189
	v_exp_f32_e64 v190, -v189
	v_add_f32_e32 v158, v158, v189
	v_pk_mul_f32 v[62:63], v[62:63], v[190:191] op_sel_hi:[1,0]
	v_pk_mul_f32 v[60:61], v[60:61], v[190:191] op_sel_hi:[1,0]
	v_pk_mul_f32 v[58:59], v[58:59], v[190:191] op_sel_hi:[1,0]
	v_pk_mul_f32 v[56:57], v[56:57], v[190:191] op_sel_hi:[1,0]
	v_pk_mul_f32 v[54:55], v[54:55], v[190:191] op_sel_hi:[1,0]
	v_pk_mul_f32 v[52:53], v[52:53], v[190:191] op_sel_hi:[1,0]
	v_pk_mul_f32 v[50:51], v[50:51], v[190:191] op_sel_hi:[1,0]
	v_pk_mul_f32 v[48:49], v[48:49], v[190:191] op_sel_hi:[1,0]
	v_pk_mul_f32 v[46:47], v[46:47], v[190:191] op_sel_hi:[1,0]
	v_pk_mul_f32 v[44:45], v[44:45], v[190:191] op_sel_hi:[1,0]
	v_pk_mul_f32 v[42:43], v[42:43], v[190:191] op_sel_hi:[1,0]
	v_pk_mul_f32 v[40:41], v[40:41], v[190:191] op_sel_hi:[1,0]
	v_pk_mul_f32 v[38:39], v[38:39], v[190:191] op_sel_hi:[1,0]
	v_pk_mul_f32 v[36:37], v[36:37], v[190:191] op_sel_hi:[1,0]
	v_pk_mul_f32 v[34:35], v[34:35], v[190:191] op_sel_hi:[1,0]
	v_pk_mul_f32 v[32:33], v[32:33], v[190:191] op_sel_hi:[1,0]
	v_pk_mul_f32 v[30:31], v[30:31], v[190:191] op_sel_hi:[1,0]
	v_pk_mul_f32 v[28:29], v[28:29], v[190:191] op_sel_hi:[1,0]
	v_pk_mul_f32 v[26:27], v[26:27], v[190:191] op_sel_hi:[1,0]
	v_pk_mul_f32 v[24:25], v[24:25], v[190:191] op_sel_hi:[1,0]
	v_pk_mul_f32 v[22:23], v[22:23], v[190:191] op_sel_hi:[1,0]
	v_pk_mul_f32 v[20:21], v[20:21], v[190:191] op_sel_hi:[1,0]
	v_pk_mul_f32 v[18:19], v[18:19], v[190:191] op_sel_hi:[1,0]
	v_pk_mul_f32 v[16:17], v[16:17], v[190:191] op_sel_hi:[1,0]
	v_pk_mul_f32 v[14:15], v[14:15], v[190:191] op_sel_hi:[1,0]
	v_pk_mul_f32 v[12:13], v[12:13], v[190:191] op_sel_hi:[1,0]
	v_pk_mul_f32 v[10:11], v[10:11], v[190:191] op_sel_hi:[1,0]
	v_pk_mul_f32 v[8:9], v[8:9], v[190:191] op_sel_hi:[1,0]
	v_pk_mul_f32 v[6:7], v[6:7], v[190:191] op_sel_hi:[1,0]
	v_pk_mul_f32 v[4:5], v[4:5], v[190:191] op_sel_hi:[1,0]
	v_pk_mul_f32 v[2:3], v[2:3], v[190:191] op_sel_hi:[1,0]
	v_pk_mul_f32 v[0:1], v[0:1], v[190:191] op_sel_hi:[1,0]
	v_mul_f32_e32 v153, v153, v190
	v_sub_f32_e32 v64, v64, v189
	v_sub_f32_e32 v65, v65, v189
	v_sub_f32_e32 v66, v66, v189
	v_sub_f32_e32 v67, v67, v189
	v_sub_f32_e32 v68, v68, v189
	v_sub_f32_e32 v69, v69, v189
	v_sub_f32_e32 v70, v70, v189
	v_sub_f32_e32 v71, v71, v189
	v_sub_f32_e32 v72, v72, v189
	v_sub_f32_e32 v73, v73, v189
	v_sub_f32_e32 v74, v74, v189
	v_sub_f32_e32 v75, v75, v189
	v_sub_f32_e32 v76, v76, v189
	v_sub_f32_e32 v77, v77, v189
	v_sub_f32_e32 v78, v78, v189
	v_sub_f32_e32 v79, v79, v189
	v_sub_f32_e32 v80, v80, v189
	v_sub_f32_e32 v81, v81, v189
	v_sub_f32_e32 v82, v82, v189
	v_sub_f32_e32 v83, v83, v189
	v_sub_f32_e32 v84, v84, v189
	v_sub_f32_e32 v85, v85, v189
	v_sub_f32_e32 v86, v86, v189
	v_sub_f32_e32 v87, v87, v189
	v_sub_f32_e32 v88, v88, v189
	v_sub_f32_e32 v89, v89, v189
	v_sub_f32_e32 v90, v90, v189
	v_sub_f32_e32 v91, v91, v189
	v_sub_f32_e32 v92, v92, v189
	v_sub_f32_e32 v93, v93, v189
	v_sub_f32_e32 v94, v94, v189
	v_sub_f32_e32 v95, v95, v189
	v_sub_f32_e32 v238, v238, v189
	v_sub_f32_e32 v239, v239, v189
	v_sub_f32_e32 v240, v240, v189
	v_sub_f32_e32 v241, v241, v189
	v_sub_f32_e32 v242, v242, v189
	v_sub_f32_e32 v243, v243, v189
	v_sub_f32_e32 v244, v244, v189
	v_sub_f32_e32 v245, v245, v189
	v_sub_f32_e32 v246, v246, v189
	v_sub_f32_e32 v247, v247, v189
	v_sub_f32_e32 v248, v248, v189
	v_sub_f32_e32 v249, v249, v189
	v_sub_f32_e32 v250, v250, v189
	v_sub_f32_e32 v251, v251, v189
	v_sub_f32_e32 v252, v252, v189
	v_sub_f32_e32 v253, v253, v189
; #define MFMA32(a, b, c) __builtin_amdgcn_mfma_f32_32x32x16_bf16((a), (b), (c), 0, 0, 0)
; #define VFRAG(ptr, off0, STR) ({ const s16x4 lo_ = vtr((ptr) + (off0)); const s16x4 hi_ = vtr((ptr) + (off0) + 8 * (STR)); (bf16x8){lo_[0], lo_[1], lo_[2], lo_[3], hi_[0], hi_[1], hi_[2], hi_[3]}; })
; __device__ __forceinline__ void diff_unit(const Frame& F, int b, int h, int qi, float lam, int dry) {
;     ...
;             float ps = 0.f;
; #pragma unroll
;             for (int r = 0; r < 16; ++r) { s0[r] = __builtin_amdgcn_exp2f(s0[r] * LOG2E - ms); ps += s0[r]; }
;             if (!meta) {
; #pragma unroll
;                 for (int r = 0; r < 16; ++r) { s1[r] = __builtin_amdgcn_exp2f(s1[r] * LOG2E - ms); ps += s1[r]; }
;             }
;             lsum += ps;
;             __builtin_amdgcn_s_setprio(1);
;             { const bf16x8 pf = pack_step(s0, 0);
;               O[0] = MFMA32(vpre0, pf, O[0]); O[1] = MFMA32(vpre1, pf, O[1]); O[2] = MFMA32(vpre2, pf, O[2]); O[3] = MFMA32(vpre3, pf, O[3]); }
;             if (!meta) {
;                 { const bf16x8 pf = pack_step(s0, 1);
;                   O[0] = MFMA32(vprf0, pf, O[0]); O[1] = MFMA32(vprf1, pf, O[1]);
; #pragma unroll
;                   for (int dt = 2; dt < 4; ++dt) { const bf16x8 vf = VFRAG(vb, 16 * DV_STR + 64 * dt, DV_STR); O[dt] = MFMA32(vf, pf, O[dt]); } }
; #pragma unroll
;                 for (int s2 = 0; s2 < 2; ++s2) { const bf16x8 pf = pack_step(s1, s2);
; #pragma unroll
;                     for (int dt = 0; dt < 4; ++dt) { const bf16x8 vf = VFRAG(vb, (32 + 16 * s2) * DV_STR + 64 * dt, DV_STR); O[dt] = MFMA32(vf, pf, O[dt]); } }
;             }
;             __builtin_amdgcn_s_setprio(0);
.LBB0_324:
	ds_read_b64_tr_b16 v[190:191], v188 offset:40064
	ds_read_b64_tr_b16 v[192:193], v188 offset:42624
	ds_read_b64_tr_b16 v[194:195], v188 offset:40128
	ds_read_b64_tr_b16 v[196:197], v188 offset:42688
	v_exp_f32_e32 v80, v80
	v_exp_f32_e32 v81, v81
	v_exp_f32_e32 v82, v82
	v_exp_f32_e32 v83, v83
	v_exp_f32_e32 v84, v84
	v_exp_f32_e32 v85, v85
	v_exp_f32_e32 v86, v86
	v_exp_f32_e32 v87, v87
	v_add_f32_e32 v202, v80, v82
	v_add_f32_e32 v203, v81, v83
	s_setprio 1
	v_cvt_pk_bf16_f32 v198, v80, v81
	v_cvt_pk_bf16_f32 v199, v82, v83
	v_cvt_pk_bf16_f32 v200, v84, v85
	v_cvt_pk_bf16_f32 v201, v86, v87
	v_add_f32_e32 v202, v202, v84
	v_add_f32_e32 v203, v203, v85
	v_add_f32_e32 v202, v202, v86
	v_add_f32_e32 v203, v203, v87
	v_mfma_f32_32x32x16_bf16 v[48:63], v[148:151], v[198:201], v[48:63]
	ds_read_b64_tr_b16 v[148:149], v188 offset:45056
	ds_read_b64_tr_b16 v[150:151], v188 offset:47616
	v_exp_f32_e32 v88, v88
	v_exp_f32_e32 v89, v89
	v_mfma_f32_32x32x16_bf16 v[32:47], v[144:147], v[198:201], v[32:47]
	ds_read_b64_tr_b16 v[144:145], v188 offset:45120
	ds_read_b64_tr_b16 v[146:147], v188 offset:47680
	v_exp_f32_e32 v90, v90
	v_exp_f32_e32 v91, v91
	v_add_f32_e32 v202, v202, v88
	v_add_f32_e32 v203, v203, v89
	v_cvt_pk_bf16_f32 v80, v88, v89
	v_mfma_f32_32x32x16_bf16 v[16:31], v[140:143], v[198:201], v[16:31]
	ds_read_b64_tr_b16 v[140:141], v188 offset:45184
	ds_read_b64_tr_b16 v[142:143], v188 offset:47744
	v_exp_f32_e32 v92, v92
	v_exp_f32_e32 v93, v93
	v_add_f32_e32 v202, v202, v90
	v_add_f32_e32 v203, v203, v91
	v_cvt_pk_bf16_f32 v81, v90, v91
	v_mfma_f32_32x32x16_bf16 v[0:15], v[136:139], v[198:201], v[0:15]
	ds_read_b64_tr_b16 v[136:137], v188 offset:45248
	ds_read_b64_tr_b16 v[138:139], v188 offset:47808
	v_exp_f32_e32 v94, v94
	v_exp_f32_e32 v95, v95
	v_add_f32_e32 v202, v202, v92
	v_add_f32_e32 v203, v203, v93
	v_cvt_pk_bf16_f32 v82, v92, v93
	v_cvt_pk_bf16_f32 v83, v94, v95
	v_add_f32_e32 v202, v202, v94
	v_add_f32_e32 v203, v203, v95
	s_nop 0
	v_mfma_f32_32x32x16_bf16 v[48:63], v[128:131], v[80:83], v[48:63]
	ds_read_b64_tr_b16 v[128:129], v188 offset:50176
	ds_read_b64_tr_b16 v[130:131], v188 offset:52736
	v_exp_f32_e32 v64, v64
	v_exp_f32_e32 v65, v65
	v_mfma_f32_32x32x16_bf16 v[32:47], v[132:135], v[80:83], v[32:47]
	ds_read_b64_tr_b16 v[132:133], v188 offset:50240
	ds_read_b64_tr_b16 v[134:135], v188 offset:52800
	v_exp_f32_e32 v66, v66
	v_exp_f32_e32 v67, v67
	v_add_f32_e32 v202, v202, v64
	v_add_f32_e32 v203, v203, v65
	v_cvt_pk_bf16_f32 v84, v64, v65
	s_waitcnt lgkmcnt(14)
	v_mfma_f32_32x32x16_bf16 v[16:31], v[190:193], v[80:83], v[16:31]
	ds_read_b64_tr_b16 v[190:191], v188 offset:50304
	ds_read_b64_tr_b16 v[192:193], v188 offset:52864
	v_exp_f32_e32 v68, v68
	v_exp_f32_e32 v69, v69
	v_add_f32_e32 v202, v202, v66
	v_add_f32_e32 v203, v203, v67
	v_cvt_pk_bf16_f32 v85, v66, v67
	s_waitcnt lgkmcnt(14)
	v_mfma_f32_32x32x16_bf16 v[0:15], v[194:197], v[80:83], v[0:15]
	ds_read_b64_tr_b16 v[194:195], v188 offset:50368
	ds_read_b64_tr_b16 v[196:197], v188 offset:52928
	v_exp_f32_e32 v70, v70
	v_exp_f32_e32 v71, v71
	v_add_f32_e32 v202, v202, v68
	v_add_f32_e32 v203, v203, v69
	v_cvt_pk_bf16_f32 v86, v68, v69
	v_cvt_pk_bf16_f32 v87, v70, v71
	v_add_f32_e32 v202, v202, v70
	v_add_f32_e32 v203, v203, v71
	s_nop 0
	s_waitcnt lgkmcnt(14)
	v_mfma_f32_32x32x16_bf16 v[48:63], v[148:151], v[84:87], v[48:63]
	v_exp_f32_e32 v72, v72
	v_exp_f32_e32 v73, v73
	s_waitcnt lgkmcnt(12)
	v_mfma_f32_32x32x16_bf16 v[32:47], v[144:147], v[84:87], v[32:47]
	v_exp_f32_e32 v74, v74
	v_exp_f32_e32 v75, v75
	v_add_f32_e32 v202, v202, v72
	v_add_f32_e32 v203, v203, v73
	v_cvt_pk_bf16_f32 v198, v72, v73
	s_waitcnt lgkmcnt(10)
	v_mfma_f32_32x32x16_bf16 v[16:31], v[140:143], v[84:87], v[16:31]
	v_exp_f32_e32 v76, v76
	v_exp_f32_e32 v77, v77
	v_add_f32_e32 v202, v202, v74
	v_add_f32_e32 v203, v203, v75
	v_cvt_pk_bf16_f32 v199, v74, v75
	s_waitcnt lgkmcnt(8)
	v_mfma_f32_32x32x16_bf16 v[0:15], v[136:139], v[84:87], v[0:15]
	v_exp_f32_e32 v78, v78
	v_exp_f32_e32 v79, v79
	v_add_f32_e32 v202, v202, v76
	v_add_f32_e32 v203, v203, v77
	v_cvt_pk_bf16_f32 v200, v76, v77
	v_cvt_pk_bf16_f32 v201, v78, v79
	v_add_f32_e32 v202, v202, v78
	v_add_f32_e32 v203, v203, v79
	v_add_f32_e32 v189, v202, v203
	v_add_f32_e32 v153, v153, v189
	s_waitcnt lgkmcnt(6)
	v_mfma_f32_32x32x16_bf16 v[48:63], v[128:131], v[198:201], v[48:63]
	s_waitcnt lgkmcnt(4)
	v_mfma_f32_32x32x16_bf16 v[32:47], v[132:135], v[198:201], v[32:47]
	s_waitcnt lgkmcnt(2)
	v_mfma_f32_32x32x16_bf16 v[16:31], v[190:193], v[198:201], v[16:31]
	s_waitcnt lgkmcnt(0)
	v_mfma_f32_32x32x16_bf16 v[0:15], v[194:197], v[198:201], v[0:15]
	s_setprio 0
	s_andn2_b64 vcc, exec, s[90:91]
	s_cbranch_vccnz .LBB0_315
